# attention: waves 4-7 start each tile 32 wait states after waves 0-3 (de-phases the two waves that share a SIMD and run the same MFMA/VALU stream)
# baseline (speedup 1.0000x reference)
.Lat_idle_0:
	s_waitcnt vmcnt(3)
	s_barrier
	s_cmp_lt_u32 s3, 4
	s_cbranch_scc1 .Lat_nd_i0
	s_nop 7
	s_nop 7
	s_nop 7
	s_nop 7

.Lat_nors_f0:
	v_fmamk_f32 v34, v34, 0x3e38aa3b, v234
	v_fmamk_f32 v35, v35, 0x3e38aa3b, v234
	s_waitcnt lgkmcnt(7)
	v_mfma_f32_32x32x16_bf16 v[70:85], v[118:121], v[102:105], 0
	ds_read_b64_tr_b16 v[154:155], v227 offset:0
	ds_read_b64_tr_b16 v[156:157], v227 offset:1024
	v_fmamk_f32 v36, v36, 0x3e38aa3b, v234
	v_fmamk_f32 v37, v37, 0x3e38aa3b, v234
	v_fmamk_f32 v38, v38, 0x3e38aa3b, v234
	v_fmamk_f32 v39, v39, 0x3e38aa3b, v234
	v_fmamk_f32 v40, v40, 0x3e38aa3b, v234
	v_fmamk_f32 v41, v41, 0x3e38aa3b, v234
	v_exp_f32_e32 v34, v34
	v_exp_f32_e32 v35, v35
	v_exp_f32_e32 v36, v36
	v_exp_f32_e32 v37, v37
	v_exp_f32_e32 v38, v38
	v_exp_f32_e32 v39, v39
	s_waitcnt lgkmcnt(8)
	v_mfma_f32_32x32x16_bf16 v[86:101], v[122:125], v[102:105], 0
	ds_read_b64_tr_b16 v[158:159], v228 offset:0
	ds_read_b64_tr_b16 v[160:161], v228 offset:1024
	v_exp_f32_e32 v40, v40
	v_exp_f32_e32 v41, v41
	v_add_f32_e32 v243, v34, v38
	v_add_f32_e32 v244, v35, v39
	v_add_f32_e32 v245, v36, v40
	v_add_f32_e32 v246, v37, v41
	v_cvt_pk_bf16_f32 v34, v34, v35
	v_cvt_pk_bf16_f32 v35, v36, v37
	v_cvt_pk_bf16_f32 v36, v38, v39
	v_cvt_pk_bf16_f32 v37, v40, v41
	v_fmamk_f32 v42, v42, 0x3e38aa3b, v234
	v_fmamk_f32 v43, v43, 0x3e38aa3b, v234
	s_waitcnt lgkmcnt(9)
	v_mfma_f32_32x32x16_bf16 v[70:85], v[126:129], v[106:109], v[70:85]
	ds_read_b64_tr_b16 v[162:163], v227 offset:2048
	ds_read_b64_tr_b16 v[164:165], v227 offset:3072
	v_fmamk_f32 v44, v44, 0x3e38aa3b, v234
	v_fmamk_f32 v45, v45, 0x3e38aa3b, v234
	v_fmamk_f32 v46, v46, 0x3e38aa3b, v234
	v_fmamk_f32 v47, v47, 0x3e38aa3b, v234
	v_fmamk_f32 v48, v48, 0x3e38aa3b, v234
	v_fmamk_f32 v49, v49, 0x3e38aa3b, v234
	v_exp_f32_e32 v42, v42
	v_exp_f32_e32 v43, v43
	v_exp_f32_e32 v44, v44
	v_exp_f32_e32 v45, v45
	v_exp_f32_e32 v46, v46
	v_exp_f32_e32 v47, v47
	s_waitcnt lgkmcnt(10)
	v_mfma_f32_32x32x16_bf16 v[86:101], v[130:133], v[106:109], v[86:101]
	ds_read_b64_tr_b16 v[166:167], v228 offset:2048
	ds_read_b64_tr_b16 v[168:169], v228 offset:3072
	v_exp_f32_e32 v48, v48
	v_exp_f32_e32 v49, v49
	v_add_f32_e32 v243, v243, v42
	v_add_f32_e32 v244, v244, v43
	v_add_f32_e32 v245, v245, v44
	v_add_f32_e32 v246, v246, v45
	v_add_f32_e32 v243, v243, v46
	v_add_f32_e32 v244, v244, v47
	v_add_f32_e32 v245, v245, v48
	v_add_f32_e32 v246, v246, v49
	v_cvt_pk_bf16_f32 v42, v42, v43
	v_cvt_pk_bf16_f32 v43, v44, v45
	s_waitcnt lgkmcnt(11)
	v_mfma_f32_32x32x16_bf16 v[70:85], v[134:137], v[110:113], v[70:85]
	ds_read_b64_tr_b16 v[170:171], v227 offset:4096
	ds_read_b64_tr_b16 v[172:173], v227 offset:5120
	v_cvt_pk_bf16_f32 v44, v46, v47
	v_cvt_pk_bf16_f32 v45, v48, v49
	v_fmamk_f32 v50, v50, 0x3e38aa3b, v234
	v_fmamk_f32 v51, v51, 0x3e38aa3b, v234
	v_fmamk_f32 v52, v52, 0x3e38aa3b, v234
	v_fmamk_f32 v53, v53, 0x3e38aa3b, v234
	v_fmamk_f32 v54, v54, 0x3e38aa3b, v234
	v_fmamk_f32 v55, v55, 0x3e38aa3b, v234
	v_fmamk_f32 v56, v56, 0x3e38aa3b, v234
	v_fmamk_f32 v57, v57, 0x3e38aa3b, v234
	v_exp_f32_e32 v50, v50
	v_exp_f32_e32 v51, v51
	s_waitcnt lgkmcnt(12)
	v_mfma_f32_32x32x16_bf16 v[86:101], v[138:141], v[110:113], v[86:101]
	ds_read_b64_tr_b16 v[174:175], v228 offset:4096
	ds_read_b64_tr_b16 v[176:177], v228 offset:5120
	v_exp_f32_e32 v52, v52
	v_exp_f32_e32 v53, v53
	v_exp_f32_e32 v54, v54
	v_exp_f32_e32 v55, v55
	v_exp_f32_e32 v56, v56
	v_exp_f32_e32 v57, v57
	v_add_f32_e32 v243, v243, v50
	v_add_f32_e32 v244, v244, v51
	v_add_f32_e32 v245, v245, v52
	v_add_f32_e32 v246, v246, v53
	v_add_f32_e32 v243, v243, v54
	v_add_f32_e32 v244, v244, v55
	s_waitcnt lgkmcnt(13)
	v_mfma_f32_32x32x16_bf16 v[70:85], v[142:145], v[114:117], v[70:85]
	ds_read_b64_tr_b16 v[178:179], v227 offset:6144
	ds_read_b64_tr_b16 v[180:181], v227 offset:7168
	v_add_f32_e32 v245, v245, v56
	v_add_f32_e32 v246, v246, v57
	v_cvt_pk_bf16_f32 v50, v50, v51
	v_cvt_pk_bf16_f32 v51, v52, v53
	v_cvt_pk_bf16_f32 v52, v54, v55
	v_cvt_pk_bf16_f32 v53, v56, v57
	v_fmamk_f32 v58, v58, 0x3e38aa3b, v234
	v_fmamk_f32 v59, v59, 0x3e38aa3b, v234
	v_fmamk_f32 v60, v60, 0x3e38aa3b, v234
	v_fmamk_f32 v61, v61, 0x3e38aa3b, v234
	v_fmamk_f32 v62, v62, 0x3e38aa3b, v234
	v_fmamk_f32 v63, v63, 0x3e38aa3b, v234
	s_waitcnt lgkmcnt(14)
	v_mfma_f32_32x32x16_bf16 v[86:101], v[146:149], v[114:117], v[86:101]
	ds_read_b64_tr_b16 v[182:183], v228 offset:6144
	ds_read_b64_tr_b16 v[184:185], v228 offset:7168
	s_waitcnt lgkmcnt(14)
	v_fmamk_f32 v64, v64, 0x3e38aa3b, v234
	v_fmamk_f32 v65, v65, 0x3e38aa3b, v234
	v_exp_f32_e32 v58, v58
	v_exp_f32_e32 v59, v59
	v_exp_f32_e32 v60, v60
	v_exp_f32_e32 v61, v61
	v_exp_f32_e32 v62, v62
	v_exp_f32_e32 v63, v63
	v_exp_f32_e32 v64, v64
	v_exp_f32_e32 v65, v65
	v_add_f32_e32 v243, v243, v58
	v_add_f32_e32 v244, v244, v59
	v_add_f32_e32 v245, v245, v60
	v_add_f32_e32 v246, v246, v61
	s_waitcnt lgkmcnt(14)
	v_mfma_f32_32x32x16_bf16 v[0:15], v[154:157], v[34:37], v[0:15]
	ds_read_b128 v[118:121], v223 offset:16384
	v_add_f32_e32 v243, v243, v62
	v_add_f32_e32 v244, v244, v63
	v_add_f32_e32 v245, v245, v64
	v_add_f32_e32 v246, v246, v65
	v_cvt_pk_bf16_f32 v58, v58, v59
	v_cvt_pk_bf16_f32 v59, v60, v61
	v_cvt_pk_bf16_f32 v60, v62, v63
	v_cvt_pk_bf16_f32 v61, v64, v65
	v_add_f32_e32 v243, v243, v244
	v_add_f32_e32 v245, v245, v246
	v_add_f32_e32 v243, v243, v245
	v_fma_f32 v231, v231, v232, v243
	s_waitcnt lgkmcnt(13)
	v_mfma_f32_32x32x16_bf16 v[16:31], v[158:161], v[34:37], v[16:31]
	ds_read_b128 v[122:125], v223 offset:20480
	v_lshrrev_b32_e32 v249, v229, v200
	v_lshrrev_b32_e32 v250, v229, v201
	v_bfe_i32 v235, v249, 0, 1
	v_bfe_i32 v236, v250, 0, 1
	v_bfe_i32 v237, v249, 1, 1
	v_bfe_i32 v238, v250, 1, 1
	v_bfe_i32 v239, v249, 2, 1
	v_bfe_i32 v240, v250, 2, 1
	v_bfe_i32 v241, v249, 3, 1
	v_bfe_i32 v242, v250, 3, 1
	v_bitop3_b32 v70, v70, s33, v235 bitop3:0xe4
	s_waitcnt lgkmcnt(12)
	v_mfma_f32_32x32x16_bf16 v[0:15], v[162:165], v[42:45], v[0:15]
	ds_read_b128 v[126:129], v224 offset:16384
	v_bitop3_b32 v86, v86, s33, v236 bitop3:0xe4
	v_bitop3_b32 v71, v71, s33, v237 bitop3:0xe4
	v_bitop3_b32 v87, v87, s33, v238 bitop3:0xe4
	v_bitop3_b32 v72, v72, s33, v239 bitop3:0xe4
	v_bitop3_b32 v88, v88, s33, v240 bitop3:0xe4
	v_bitop3_b32 v73, v73, s33, v241 bitop3:0xe4
	v_bitop3_b32 v89, v89, s33, v242 bitop3:0xe4
	v_max3_f32 v247, v70, s33, v86
	v_max3_f32 v248, v71, s33, v87
	v_max3_f32 v247, v247, v72, v88
	v_max3_f32 v248, v248, v73, v89
	v_bfe_i32 v235, v249, 8, 1
	s_waitcnt lgkmcnt(11)
	v_mfma_f32_32x32x16_bf16 v[16:31], v[166:169], v[42:45], v[16:31]
	ds_read_b128 v[130:133], v224 offset:20480
	v_bfe_i32 v236, v250, 8, 1
	v_bfe_i32 v237, v249, 9, 1
	v_bfe_i32 v238, v250, 9, 1
	v_bfe_i32 v239, v249, 10, 1
	v_bfe_i32 v240, v250, 10, 1
	v_bfe_i32 v241, v249, 11, 1
	v_bfe_i32 v242, v250, 11, 1
	v_bitop3_b32 v74, v74, s33, v235 bitop3:0xe4
	v_bitop3_b32 v90, v90, s33, v236 bitop3:0xe4
	v_bitop3_b32 v75, v75, s33, v237 bitop3:0xe4
	v_bitop3_b32 v91, v91, s33, v238 bitop3:0xe4
	v_bitop3_b32 v76, v76, s33, v239 bitop3:0xe4
	s_waitcnt lgkmcnt(10)
	v_mfma_f32_32x32x16_bf16 v[0:15], v[170:173], v[50:53], v[0:15]
	ds_read_b128 v[134:137], v225 offset:16384
	v_bitop3_b32 v92, v92, s33, v240 bitop3:0xe4
	v_bitop3_b32 v77, v77, s33, v241 bitop3:0xe4
	v_bitop3_b32 v93, v93, s33, v242 bitop3:0xe4
	v_max3_f32 v247, v247, v74, v90
	v_max3_f32 v248, v248, v75, v91
	v_max3_f32 v247, v247, v76, v92
	v_max3_f32 v248, v248, v77, v93
	v_bfe_i32 v235, v249, 16, 1
	v_bfe_i32 v236, v250, 16, 1
	v_bfe_i32 v237, v249, 17, 1
	v_bfe_i32 v238, v250, 17, 1
	v_bfe_i32 v239, v249, 18, 1
	s_waitcnt lgkmcnt(9)
	v_mfma_f32_32x32x16_bf16 v[16:31], v[174:177], v[50:53], v[16:31]
	ds_read_b128 v[138:141], v225 offset:20480
	v_bfe_i32 v240, v250, 18, 1
	v_bfe_i32 v241, v249, 19, 1
	v_bfe_i32 v242, v250, 19, 1
	v_bitop3_b32 v78, v78, s33, v235 bitop3:0xe4
	v_bitop3_b32 v94, v94, s33, v236 bitop3:0xe4
	v_bitop3_b32 v79, v79, s33, v237 bitop3:0xe4
	v_bitop3_b32 v95, v95, s33, v238 bitop3:0xe4
	v_bitop3_b32 v80, v80, s33, v239 bitop3:0xe4
	v_bitop3_b32 v96, v96, s33, v240 bitop3:0xe4
	v_bitop3_b32 v81, v81, s33, v241 bitop3:0xe4
	v_bitop3_b32 v97, v97, s33, v242 bitop3:0xe4
	v_max3_f32 v247, v247, v78, v94
	s_waitcnt lgkmcnt(8)
	v_mfma_f32_32x32x16_bf16 v[0:15], v[178:181], v[58:61], v[0:15]
	ds_read_b128 v[142:145], v226 offset:16384
	v_max3_f32 v248, v248, v79, v95
	v_max3_f32 v247, v247, v80, v96
	v_max3_f32 v248, v248, v81, v97
	v_bfe_i32 v235, v249, 24, 1
	v_bfe_i32 v236, v250, 24, 1
	v_bfe_i32 v237, v249, 25, 1
	v_bfe_i32 v238, v250, 25, 1
	v_bfe_i32 v239, v249, 26, 1
	v_bfe_i32 v240, v250, 26, 1
	v_bfe_i32 v241, v249, 27, 1
	v_bfe_i32 v242, v250, 27, 1
	v_bitop3_b32 v82, v82, s33, v235 bitop3:0xe4
	s_waitcnt lgkmcnt(7)
	v_mfma_f32_32x32x16_bf16 v[16:31], v[182:185], v[58:61], v[16:31]
	ds_read_b128 v[146:149], v226 offset:20480
	v_bitop3_b32 v98, v98, s33, v236 bitop3:0xe4
	v_bitop3_b32 v83, v83, s33, v237 bitop3:0xe4
	v_bitop3_b32 v99, v99, s33, v238 bitop3:0xe4
	v_bitop3_b32 v84, v84, s33, v239 bitop3:0xe4
	v_bitop3_b32 v100, v100, s33, v240 bitop3:0xe4
	v_bitop3_b32 v85, v85, s33, v241 bitop3:0xe4
	v_bitop3_b32 v101, v101, s33, v242 bitop3:0xe4
	v_max3_f32 v247, v247, v82, v98
	v_max3_f32 v248, v248, v83, v99
	v_max3_f32 v247, v247, v84, v100
	v_max3_f32 v248, v248, v85, v101
	v_max_f32_e32 v247, v247, v248
	v_mov_b32_e32 v248, v247
	s_nop 1
	v_permlane32_swap_b32_e32 v247, v248
	v_max3_f32 v247, v230, v247, v248
	v_cmp_neq_f32_e32 vcc, s33, v247
	s_nop 1
	v_cndmask_b32_e32 v248, 0, v247, vcc
	v_sub_f32_e32 v33, v230, v248
	v_mul_f32_e32 v33, 0x3e38aa3b, v33
	v_exp_f32_e32 v232, v33
	v_mul_f32_e32 v234, 0xbe38aa3b, v248
	v_mov_b32_e32 v230, v247
	s_waitcnt vmcnt(3)
	s_barrier
	s_cmp_lt_u32 s3, 4
	s_cbranch_scc1 .Lat_nd_f0
	s_nop 7
	s_nop 7
	s_nop 7
	s_nop 7

.Lat_nors_l0:
	v_fmamk_f32 v34, v34, 0x3e38aa3b, v234
	v_fmamk_f32 v35, v35, 0x3e38aa3b, v234
	v_fmamk_f32 v36, v36, 0x3e38aa3b, v234
	ds_read_b64_tr_b16 v[168:169], v228 offset:3072
	s_waitcnt lgkmcnt(14)
	v_fmamk_f32 v37, v37, 0x3e38aa3b, v234
	v_fmamk_f32 v38, v38, 0x3e38aa3b, v234
	v_fmamk_f32 v39, v39, 0x3e38aa3b, v234
	ds_read_b64_tr_b16 v[170:171], v227 offset:4096
	s_waitcnt lgkmcnt(14)
	v_fmamk_f32 v40, v40, 0x3e38aa3b, v234
	v_fmamk_f32 v41, v41, 0x3e38aa3b, v234
	v_exp_f32_e32 v34, v34
	ds_read_b64_tr_b16 v[172:173], v227 offset:5120
	s_waitcnt lgkmcnt(14)
	v_exp_f32_e32 v35, v35
	v_exp_f32_e32 v36, v36
	v_exp_f32_e32 v37, v37
	ds_read_b64_tr_b16 v[174:175], v228 offset:4096
	s_waitcnt lgkmcnt(14)
	v_exp_f32_e32 v38, v38
	v_exp_f32_e32 v39, v39
	v_exp_f32_e32 v40, v40
	ds_read_b64_tr_b16 v[176:177], v228 offset:5120
	s_waitcnt lgkmcnt(14)
	v_exp_f32_e32 v41, v41
	v_add_f32_e32 v243, v34, v38
	v_add_f32_e32 v244, v35, v39
	ds_read_b64_tr_b16 v[178:179], v227 offset:6144
	s_waitcnt lgkmcnt(14)
	v_add_f32_e32 v245, v36, v40
	v_add_f32_e32 v246, v37, v41
	v_cvt_pk_bf16_f32 v34, v34, v35
	ds_read_b64_tr_b16 v[180:181], v227 offset:7168
	s_waitcnt lgkmcnt(14)
	v_cvt_pk_bf16_f32 v35, v36, v37
	v_cvt_pk_bf16_f32 v36, v38, v39
	v_cvt_pk_bf16_f32 v37, v40, v41
	ds_read_b64_tr_b16 v[182:183], v228 offset:6144
	s_waitcnt lgkmcnt(14)
	s_waitcnt lgkmcnt(13)
	v_mfma_f32_32x32x16_bf16 v[0:15], v[154:157], v[34:37], v[0:15]
	s_waitcnt lgkmcnt(11)
	v_mfma_f32_32x32x16_bf16 v[16:31], v[158:161], v[34:37], v[16:31]
	v_fmamk_f32 v42, v42, 0x3e38aa3b, v234
	v_fmamk_f32 v43, v43, 0x3e38aa3b, v234
	v_fmamk_f32 v44, v44, 0x3e38aa3b, v234
	ds_read_b64_tr_b16 v[184:185], v228 offset:7168
	v_fmamk_f32 v45, v45, 0x3e38aa3b, v234
	v_fmamk_f32 v46, v46, 0x3e38aa3b, v234
	v_fmamk_f32 v47, v47, 0x3e38aa3b, v234
	v_fmamk_f32 v48, v48, 0x3e38aa3b, v234
	v_fmamk_f32 v49, v49, 0x3e38aa3b, v234
	v_exp_f32_e32 v42, v42
	v_exp_f32_e32 v43, v43
	v_exp_f32_e32 v44, v44
	v_exp_f32_e32 v45, v45
	v_exp_f32_e32 v46, v46
	v_exp_f32_e32 v47, v47
	v_exp_f32_e32 v48, v48
	v_exp_f32_e32 v49, v49
	v_add_f32_e32 v243, v243, v42
	v_add_f32_e32 v244, v244, v43
	v_add_f32_e32 v245, v245, v44
	v_add_f32_e32 v246, v246, v45
	v_add_f32_e32 v243, v243, v46
	v_add_f32_e32 v244, v244, v47
	v_add_f32_e32 v245, v245, v48
	v_add_f32_e32 v246, v246, v49
	v_cvt_pk_bf16_f32 v42, v42, v43
	v_cvt_pk_bf16_f32 v43, v44, v45
	v_cvt_pk_bf16_f32 v44, v46, v47
	v_cvt_pk_bf16_f32 v45, v48, v49
	s_waitcnt lgkmcnt(10)
	v_mfma_f32_32x32x16_bf16 v[0:15], v[162:165], v[42:45], v[0:15]
	s_waitcnt lgkmcnt(8)
	v_mfma_f32_32x32x16_bf16 v[16:31], v[166:169], v[42:45], v[16:31]
	v_fmamk_f32 v50, v50, 0x3e38aa3b, v234
	v_fmamk_f32 v51, v51, 0x3e38aa3b, v234
	v_fmamk_f32 v52, v52, 0x3e38aa3b, v234
	v_fmamk_f32 v53, v53, 0x3e38aa3b, v234
	v_fmamk_f32 v54, v54, 0x3e38aa3b, v234
	v_fmamk_f32 v55, v55, 0x3e38aa3b, v234
	v_fmamk_f32 v56, v56, 0x3e38aa3b, v234
	v_fmamk_f32 v57, v57, 0x3e38aa3b, v234
	v_exp_f32_e32 v50, v50
	v_exp_f32_e32 v51, v51
	v_exp_f32_e32 v52, v52
	v_exp_f32_e32 v53, v53
	v_exp_f32_e32 v54, v54
	v_exp_f32_e32 v55, v55
	v_exp_f32_e32 v56, v56
	v_exp_f32_e32 v57, v57
	v_add_f32_e32 v243, v243, v50
	v_add_f32_e32 v244, v244, v51
	v_add_f32_e32 v245, v245, v52
	v_add_f32_e32 v246, v246, v53
	v_add_f32_e32 v243, v243, v54
	v_add_f32_e32 v244, v244, v55
	v_add_f32_e32 v245, v245, v56
	v_add_f32_e32 v246, v246, v57
	v_cvt_pk_bf16_f32 v50, v50, v51
	v_cvt_pk_bf16_f32 v51, v52, v53
	v_cvt_pk_bf16_f32 v52, v54, v55
	v_cvt_pk_bf16_f32 v53, v56, v57
	s_waitcnt lgkmcnt(6)
	v_mfma_f32_32x32x16_bf16 v[0:15], v[170:173], v[50:53], v[0:15]
	s_waitcnt lgkmcnt(4)
	v_mfma_f32_32x32x16_bf16 v[16:31], v[174:177], v[50:53], v[16:31]
	v_fmamk_f32 v58, v58, 0x3e38aa3b, v234
	v_fmamk_f32 v59, v59, 0x3e38aa3b, v234
	v_fmamk_f32 v60, v60, 0x3e38aa3b, v234
	v_fmamk_f32 v61, v61, 0x3e38aa3b, v234
	v_fmamk_f32 v62, v62, 0x3e38aa3b, v234
	v_fmamk_f32 v63, v63, 0x3e38aa3b, v234
	v_fmamk_f32 v64, v64, 0x3e38aa3b, v234
	v_fmamk_f32 v65, v65, 0x3e38aa3b, v234
	v_exp_f32_e32 v58, v58
	v_exp_f32_e32 v59, v59
	v_exp_f32_e32 v60, v60
	v_exp_f32_e32 v61, v61
	v_exp_f32_e32 v62, v62
	v_exp_f32_e32 v63, v63
	v_exp_f32_e32 v64, v64
	v_exp_f32_e32 v65, v65
	v_add_f32_e32 v243, v243, v58
	v_add_f32_e32 v244, v244, v59
	v_add_f32_e32 v245, v245, v60
	v_add_f32_e32 v246, v246, v61
	v_add_f32_e32 v243, v243, v62
	v_add_f32_e32 v244, v244, v63
	v_add_f32_e32 v245, v245, v64
	v_add_f32_e32 v246, v246, v65
	v_cvt_pk_bf16_f32 v58, v58, v59
	v_cvt_pk_bf16_f32 v59, v60, v61
	v_cvt_pk_bf16_f32 v60, v62, v63
	v_cvt_pk_bf16_f32 v61, v64, v65
	v_add_f32_e32 v243, v243, v244
	v_add_f32_e32 v245, v245, v246
	v_add_f32_e32 v243, v243, v245
	v_fma_f32 v231, v231, v232, v243
	s_waitcnt lgkmcnt(2)
	v_mfma_f32_32x32x16_bf16 v[0:15], v[178:181], v[58:61], v[0:15]
	s_waitcnt lgkmcnt(0)
	v_mfma_f32_32x32x16_bf16 v[16:31], v[182:185], v[58:61], v[16:31]
	s_waitcnt vmcnt(3)
	s_barrier
	s_cmp_lt_u32 s3, 4
	s_cbranch_scc1 .Lat_nd_l0
	s_nop 7
	s_nop 7
	s_nop 7
	s_nop 7

.Lat_idle_1:
	s_waitcnt vmcnt(2)
	s_barrier
	s_cmp_lt_u32 s3, 4
	s_cbranch_scc1 .Lat_nd_i1
	s_nop 7
	s_nop 7
	s_nop 7
	s_nop 7

.Lat_nors_f1:
	v_fmamk_f32 v70, v70, 0x3e38aa3b, v234
	v_fmamk_f32 v71, v71, 0x3e38aa3b, v234
	s_waitcnt lgkmcnt(7)
	v_mfma_f32_32x32x16_bf16 v[34:49], v[118:121], v[102:105], 0
	ds_read_b64_tr_b16 v[154:155], v227 offset:8192
	ds_read_b64_tr_b16 v[156:157], v227 offset:9216
	v_fmamk_f32 v72, v72, 0x3e38aa3b, v234
	v_fmamk_f32 v73, v73, 0x3e38aa3b, v234
	v_fmamk_f32 v74, v74, 0x3e38aa3b, v234
	v_fmamk_f32 v75, v75, 0x3e38aa3b, v234
	v_fmamk_f32 v76, v76, 0x3e38aa3b, v234
	v_fmamk_f32 v77, v77, 0x3e38aa3b, v234
	v_exp_f32_e32 v70, v70
	v_exp_f32_e32 v71, v71
	v_exp_f32_e32 v72, v72
	v_exp_f32_e32 v73, v73
	v_exp_f32_e32 v74, v74
	v_exp_f32_e32 v75, v75
	s_waitcnt lgkmcnt(8)
	v_mfma_f32_32x32x16_bf16 v[50:65], v[122:125], v[102:105], 0
	ds_read_b64_tr_b16 v[158:159], v228 offset:8192
	ds_read_b64_tr_b16 v[160:161], v228 offset:9216
	v_exp_f32_e32 v76, v76
	v_exp_f32_e32 v77, v77
	v_add_f32_e32 v243, v70, v74
	v_add_f32_e32 v244, v71, v75
	v_add_f32_e32 v245, v72, v76
	v_add_f32_e32 v246, v73, v77
	v_cvt_pk_bf16_f32 v70, v70, v71
	v_cvt_pk_bf16_f32 v71, v72, v73
	v_cvt_pk_bf16_f32 v72, v74, v75
	v_cvt_pk_bf16_f32 v73, v76, v77
	v_fmamk_f32 v78, v78, 0x3e38aa3b, v234
	v_fmamk_f32 v79, v79, 0x3e38aa3b, v234
	s_waitcnt lgkmcnt(9)
	v_mfma_f32_32x32x16_bf16 v[34:49], v[126:129], v[106:109], v[34:49]
	ds_read_b64_tr_b16 v[162:163], v227 offset:10240
	ds_read_b64_tr_b16 v[164:165], v227 offset:11264
	v_fmamk_f32 v80, v80, 0x3e38aa3b, v234
	v_fmamk_f32 v81, v81, 0x3e38aa3b, v234
	v_fmamk_f32 v82, v82, 0x3e38aa3b, v234
	v_fmamk_f32 v83, v83, 0x3e38aa3b, v234
	v_fmamk_f32 v84, v84, 0x3e38aa3b, v234
	v_fmamk_f32 v85, v85, 0x3e38aa3b, v234
	v_exp_f32_e32 v78, v78
	v_exp_f32_e32 v79, v79
	v_exp_f32_e32 v80, v80
	v_exp_f32_e32 v81, v81
	v_exp_f32_e32 v82, v82
	v_exp_f32_e32 v83, v83
	s_waitcnt lgkmcnt(10)
	v_mfma_f32_32x32x16_bf16 v[50:65], v[130:133], v[106:109], v[50:65]
	ds_read_b64_tr_b16 v[166:167], v228 offset:10240
	ds_read_b64_tr_b16 v[168:169], v228 offset:11264
	v_exp_f32_e32 v84, v84
	v_exp_f32_e32 v85, v85
	v_add_f32_e32 v243, v243, v78
	v_add_f32_e32 v244, v244, v79
	v_add_f32_e32 v245, v245, v80
	v_add_f32_e32 v246, v246, v81
	v_add_f32_e32 v243, v243, v82
	v_add_f32_e32 v244, v244, v83
	v_add_f32_e32 v245, v245, v84
	v_add_f32_e32 v246, v246, v85
	v_cvt_pk_bf16_f32 v78, v78, v79
	v_cvt_pk_bf16_f32 v79, v80, v81
	s_waitcnt lgkmcnt(11)
	v_mfma_f32_32x32x16_bf16 v[34:49], v[134:137], v[110:113], v[34:49]
	ds_read_b64_tr_b16 v[170:171], v227 offset:12288
	ds_read_b64_tr_b16 v[172:173], v227 offset:13312
	v_cvt_pk_bf16_f32 v80, v82, v83
	v_cvt_pk_bf16_f32 v81, v84, v85
	v_fmamk_f32 v86, v86, 0x3e38aa3b, v234
	v_fmamk_f32 v87, v87, 0x3e38aa3b, v234
	v_fmamk_f32 v88, v88, 0x3e38aa3b, v234
	v_fmamk_f32 v89, v89, 0x3e38aa3b, v234
	v_fmamk_f32 v90, v90, 0x3e38aa3b, v234
	v_fmamk_f32 v91, v91, 0x3e38aa3b, v234
	v_fmamk_f32 v92, v92, 0x3e38aa3b, v234
	v_fmamk_f32 v93, v93, 0x3e38aa3b, v234
	v_exp_f32_e32 v86, v86
	v_exp_f32_e32 v87, v87
	s_waitcnt lgkmcnt(12)
	v_mfma_f32_32x32x16_bf16 v[50:65], v[138:141], v[110:113], v[50:65]
	ds_read_b64_tr_b16 v[174:175], v228 offset:12288
	ds_read_b64_tr_b16 v[176:177], v228 offset:13312
	v_exp_f32_e32 v88, v88
	v_exp_f32_e32 v89, v89
	v_exp_f32_e32 v90, v90
	v_exp_f32_e32 v91, v91
	v_exp_f32_e32 v92, v92
	v_exp_f32_e32 v93, v93
	v_add_f32_e32 v243, v243, v86
	v_add_f32_e32 v244, v244, v87
	v_add_f32_e32 v245, v245, v88
	v_add_f32_e32 v246, v246, v89
	v_add_f32_e32 v243, v243, v90
	v_add_f32_e32 v244, v244, v91
	s_waitcnt lgkmcnt(13)
	v_mfma_f32_32x32x16_bf16 v[34:49], v[142:145], v[114:117], v[34:49]
	ds_read_b64_tr_b16 v[178:179], v227 offset:14336
	ds_read_b64_tr_b16 v[180:181], v227 offset:15360
	v_add_f32_e32 v245, v245, v92
	v_add_f32_e32 v246, v246, v93
	v_cvt_pk_bf16_f32 v86, v86, v87
	v_cvt_pk_bf16_f32 v87, v88, v89
	v_cvt_pk_bf16_f32 v88, v90, v91
	v_cvt_pk_bf16_f32 v89, v92, v93
	v_fmamk_f32 v94, v94, 0x3e38aa3b, v234
	v_fmamk_f32 v95, v95, 0x3e38aa3b, v234
	v_fmamk_f32 v96, v96, 0x3e38aa3b, v234
	v_fmamk_f32 v97, v97, 0x3e38aa3b, v234
	v_fmamk_f32 v98, v98, 0x3e38aa3b, v234
	v_fmamk_f32 v99, v99, 0x3e38aa3b, v234
	s_waitcnt lgkmcnt(14)
	v_mfma_f32_32x32x16_bf16 v[50:65], v[146:149], v[114:117], v[50:65]
	ds_read_b64_tr_b16 v[182:183], v228 offset:14336
	ds_read_b64_tr_b16 v[184:185], v228 offset:15360
	s_waitcnt lgkmcnt(14)
	v_fmamk_f32 v100, v100, 0x3e38aa3b, v234
	v_fmamk_f32 v101, v101, 0x3e38aa3b, v234
	v_exp_f32_e32 v94, v94
	v_exp_f32_e32 v95, v95
	v_exp_f32_e32 v96, v96
	v_exp_f32_e32 v97, v97
	v_exp_f32_e32 v98, v98
	v_exp_f32_e32 v99, v99
	v_exp_f32_e32 v100, v100
	v_exp_f32_e32 v101, v101
	v_add_f32_e32 v243, v243, v94
	v_add_f32_e32 v244, v244, v95
	v_add_f32_e32 v245, v245, v96
	v_add_f32_e32 v246, v246, v97
	s_waitcnt lgkmcnt(14)
	v_mfma_f32_32x32x16_bf16 v[0:15], v[154:157], v[70:73], v[0:15]
	ds_read_b128 v[118:121], v223 offset:24576
	v_add_f32_e32 v243, v243, v98
	v_add_f32_e32 v244, v244, v99
	v_add_f32_e32 v245, v245, v100
	v_add_f32_e32 v246, v246, v101
	v_cvt_pk_bf16_f32 v94, v94, v95
	v_cvt_pk_bf16_f32 v95, v96, v97
	v_cvt_pk_bf16_f32 v96, v98, v99
	v_cvt_pk_bf16_f32 v97, v100, v101
	v_add_f32_e32 v243, v243, v244
	v_add_f32_e32 v245, v245, v246
	v_add_f32_e32 v243, v243, v245
	v_fma_f32 v231, v231, v232, v243
	s_waitcnt lgkmcnt(13)
	v_mfma_f32_32x32x16_bf16 v[16:31], v[158:161], v[70:73], v[16:31]
	ds_read_b128 v[122:125], v223 offset:28672
	s_waitcnt vmcnt(4)
	v_lshrrev_b32_e32 v249, v229, v202
	v_lshrrev_b32_e32 v250, v229, v203
	v_bfe_i32 v235, v249, 0, 1
	v_bfe_i32 v236, v250, 0, 1
	v_bfe_i32 v237, v249, 1, 1
	v_bfe_i32 v238, v250, 1, 1
	v_bfe_i32 v239, v249, 2, 1
	v_bfe_i32 v240, v250, 2, 1
	v_bfe_i32 v241, v249, 3, 1
	v_bfe_i32 v242, v250, 3, 1
	v_bitop3_b32 v34, v34, s33, v235 bitop3:0xe4
	s_waitcnt lgkmcnt(12)
	v_mfma_f32_32x32x16_bf16 v[0:15], v[162:165], v[78:81], v[0:15]
	ds_read_b128 v[126:129], v224 offset:24576
	v_bitop3_b32 v50, v50, s33, v236 bitop3:0xe4
	v_bitop3_b32 v35, v35, s33, v237 bitop3:0xe4
	v_bitop3_b32 v51, v51, s33, v238 bitop3:0xe4
	v_bitop3_b32 v36, v36, s33, v239 bitop3:0xe4
	v_bitop3_b32 v52, v52, s33, v240 bitop3:0xe4
	v_bitop3_b32 v37, v37, s33, v241 bitop3:0xe4
	v_bitop3_b32 v53, v53, s33, v242 bitop3:0xe4
	v_max3_f32 v247, v34, s33, v50
	v_max3_f32 v248, v35, s33, v51
	v_max3_f32 v247, v247, v36, v52
	v_max3_f32 v248, v248, v37, v53
	v_bfe_i32 v235, v249, 8, 1
	s_waitcnt lgkmcnt(11)
	v_mfma_f32_32x32x16_bf16 v[16:31], v[166:169], v[78:81], v[16:31]
	ds_read_b128 v[130:133], v224 offset:28672
	v_bfe_i32 v236, v250, 8, 1
	v_bfe_i32 v237, v249, 9, 1
	v_bfe_i32 v238, v250, 9, 1
	v_bfe_i32 v239, v249, 10, 1
	v_bfe_i32 v240, v250, 10, 1
	v_bfe_i32 v241, v249, 11, 1
	v_bfe_i32 v242, v250, 11, 1
	v_bitop3_b32 v38, v38, s33, v235 bitop3:0xe4
	v_bitop3_b32 v54, v54, s33, v236 bitop3:0xe4
	v_bitop3_b32 v39, v39, s33, v237 bitop3:0xe4
	v_bitop3_b32 v55, v55, s33, v238 bitop3:0xe4
	v_bitop3_b32 v40, v40, s33, v239 bitop3:0xe4
	s_waitcnt lgkmcnt(10)
	v_mfma_f32_32x32x16_bf16 v[0:15], v[170:173], v[86:89], v[0:15]
	ds_read_b128 v[134:137], v225 offset:24576
	v_bitop3_b32 v56, v56, s33, v240 bitop3:0xe4
	v_bitop3_b32 v41, v41, s33, v241 bitop3:0xe4
	v_bitop3_b32 v57, v57, s33, v242 bitop3:0xe4
	v_max3_f32 v247, v247, v38, v54
	v_max3_f32 v248, v248, v39, v55
	v_max3_f32 v247, v247, v40, v56
	v_max3_f32 v248, v248, v41, v57
	v_bfe_i32 v235, v249, 16, 1
	v_bfe_i32 v236, v250, 16, 1
	v_bfe_i32 v237, v249, 17, 1
	v_bfe_i32 v238, v250, 17, 1
	v_bfe_i32 v239, v249, 18, 1
	s_waitcnt lgkmcnt(9)
	v_mfma_f32_32x32x16_bf16 v[16:31], v[174:177], v[86:89], v[16:31]
	ds_read_b128 v[138:141], v225 offset:28672
	v_bfe_i32 v240, v250, 18, 1
	v_bfe_i32 v241, v249, 19, 1
	v_bfe_i32 v242, v250, 19, 1
	v_bitop3_b32 v42, v42, s33, v235 bitop3:0xe4
	v_bitop3_b32 v58, v58, s33, v236 bitop3:0xe4
	v_bitop3_b32 v43, v43, s33, v237 bitop3:0xe4
	v_bitop3_b32 v59, v59, s33, v238 bitop3:0xe4
	v_bitop3_b32 v44, v44, s33, v239 bitop3:0xe4
	v_bitop3_b32 v60, v60, s33, v240 bitop3:0xe4
	v_bitop3_b32 v45, v45, s33, v241 bitop3:0xe4
	v_bitop3_b32 v61, v61, s33, v242 bitop3:0xe4
	v_max3_f32 v247, v247, v42, v58
	s_waitcnt lgkmcnt(8)
	v_mfma_f32_32x32x16_bf16 v[0:15], v[178:181], v[94:97], v[0:15]
	ds_read_b128 v[142:145], v226 offset:24576
	v_max3_f32 v248, v248, v43, v59
	v_max3_f32 v247, v247, v44, v60
	v_max3_f32 v248, v248, v45, v61
	v_bfe_i32 v235, v249, 24, 1
	v_bfe_i32 v236, v250, 24, 1
	v_bfe_i32 v237, v249, 25, 1
	v_bfe_i32 v238, v250, 25, 1
	v_bfe_i32 v239, v249, 26, 1
	v_bfe_i32 v240, v250, 26, 1
	v_bfe_i32 v241, v249, 27, 1
	v_bfe_i32 v242, v250, 27, 1
	v_bitop3_b32 v46, v46, s33, v235 bitop3:0xe4
	s_waitcnt lgkmcnt(7)
	v_mfma_f32_32x32x16_bf16 v[16:31], v[182:185], v[94:97], v[16:31]
	ds_read_b128 v[146:149], v226 offset:28672
	v_bitop3_b32 v62, v62, s33, v236 bitop3:0xe4
	v_bitop3_b32 v47, v47, s33, v237 bitop3:0xe4
	v_bitop3_b32 v63, v63, s33, v238 bitop3:0xe4
	v_bitop3_b32 v48, v48, s33, v239 bitop3:0xe4
	v_bitop3_b32 v64, v64, s33, v240 bitop3:0xe4
	v_bitop3_b32 v49, v49, s33, v241 bitop3:0xe4
	v_bitop3_b32 v65, v65, s33, v242 bitop3:0xe4
	v_max3_f32 v247, v247, v46, v62
	v_max3_f32 v248, v248, v47, v63
	v_max3_f32 v247, v247, v48, v64
	v_max3_f32 v248, v248, v49, v65
	v_max_f32_e32 v247, v247, v248
	v_mov_b32_e32 v248, v247
	s_nop 1
	v_permlane32_swap_b32_e32 v247, v248
	v_max3_f32 v247, v230, v247, v248
	v_cmp_neq_f32_e32 vcc, s33, v247
	s_nop 1
	v_cndmask_b32_e32 v248, 0, v247, vcc
	v_sub_f32_e32 v33, v230, v248
	v_mul_f32_e32 v33, 0x3e38aa3b, v33
	v_exp_f32_e32 v232, v33
	v_mul_f32_e32 v234, 0xbe38aa3b, v248
	v_mov_b32_e32 v230, v247
	s_waitcnt vmcnt(2)
	s_barrier
	s_cmp_lt_u32 s3, 4
	s_cbranch_scc1 .Lat_nd_f1
	s_nop 7
	s_nop 7
	s_nop 7
	s_nop 7

.Lat_nors_l1:
	v_fmamk_f32 v70, v70, 0x3e38aa3b, v234
	v_fmamk_f32 v71, v71, 0x3e38aa3b, v234
	v_fmamk_f32 v72, v72, 0x3e38aa3b, v234
	ds_read_b64_tr_b16 v[168:169], v228 offset:11264
	s_waitcnt lgkmcnt(14)
	v_fmamk_f32 v73, v73, 0x3e38aa3b, v234
	v_fmamk_f32 v74, v74, 0x3e38aa3b, v234
	v_fmamk_f32 v75, v75, 0x3e38aa3b, v234
	ds_read_b64_tr_b16 v[170:171], v227 offset:12288
	s_waitcnt lgkmcnt(14)
	v_fmamk_f32 v76, v76, 0x3e38aa3b, v234
	v_fmamk_f32 v77, v77, 0x3e38aa3b, v234
	v_exp_f32_e32 v70, v70
	ds_read_b64_tr_b16 v[172:173], v227 offset:13312
	s_waitcnt lgkmcnt(14)
	v_exp_f32_e32 v71, v71
	v_exp_f32_e32 v72, v72
	v_exp_f32_e32 v73, v73
	ds_read_b64_tr_b16 v[174:175], v228 offset:12288
	s_waitcnt lgkmcnt(14)
	v_exp_f32_e32 v74, v74
	v_exp_f32_e32 v75, v75
	v_exp_f32_e32 v76, v76
	ds_read_b64_tr_b16 v[176:177], v228 offset:13312
	s_waitcnt lgkmcnt(14)
	v_exp_f32_e32 v77, v77
	v_add_f32_e32 v243, v70, v74
	v_add_f32_e32 v244, v71, v75
	ds_read_b64_tr_b16 v[178:179], v227 offset:14336
	s_waitcnt lgkmcnt(14)
	v_add_f32_e32 v245, v72, v76
	v_add_f32_e32 v246, v73, v77
	v_cvt_pk_bf16_f32 v70, v70, v71
	ds_read_b64_tr_b16 v[180:181], v227 offset:15360
	s_waitcnt lgkmcnt(14)
	v_cvt_pk_bf16_f32 v71, v72, v73
	v_cvt_pk_bf16_f32 v72, v74, v75
	v_cvt_pk_bf16_f32 v73, v76, v77
	ds_read_b64_tr_b16 v[182:183], v228 offset:14336
	s_waitcnt lgkmcnt(14)
	s_waitcnt lgkmcnt(13)
	v_mfma_f32_32x32x16_bf16 v[0:15], v[154:157], v[70:73], v[0:15]
	s_waitcnt lgkmcnt(11)
	v_mfma_f32_32x32x16_bf16 v[16:31], v[158:161], v[70:73], v[16:31]
	v_fmamk_f32 v78, v78, 0x3e38aa3b, v234
	v_fmamk_f32 v79, v79, 0x3e38aa3b, v234
	v_fmamk_f32 v80, v80, 0x3e38aa3b, v234
	ds_read_b64_tr_b16 v[184:185], v228 offset:15360
	v_fmamk_f32 v81, v81, 0x3e38aa3b, v234
	v_fmamk_f32 v82, v82, 0x3e38aa3b, v234
	v_fmamk_f32 v83, v83, 0x3e38aa3b, v234
	v_fmamk_f32 v84, v84, 0x3e38aa3b, v234
	v_fmamk_f32 v85, v85, 0x3e38aa3b, v234
	v_exp_f32_e32 v78, v78
	v_exp_f32_e32 v79, v79
	v_exp_f32_e32 v80, v80
	v_exp_f32_e32 v81, v81
	v_exp_f32_e32 v82, v82
	v_exp_f32_e32 v83, v83
	v_exp_f32_e32 v84, v84
	v_exp_f32_e32 v85, v85
	v_add_f32_e32 v243, v243, v78
	v_add_f32_e32 v244, v244, v79
	v_add_f32_e32 v245, v245, v80
	v_add_f32_e32 v246, v246, v81
	v_add_f32_e32 v243, v243, v82
	v_add_f32_e32 v244, v244, v83
	v_add_f32_e32 v245, v245, v84
	v_add_f32_e32 v246, v246, v85
	v_cvt_pk_bf16_f32 v78, v78, v79
	v_cvt_pk_bf16_f32 v79, v80, v81
	v_cvt_pk_bf16_f32 v80, v82, v83
	v_cvt_pk_bf16_f32 v81, v84, v85
	s_waitcnt lgkmcnt(10)
	v_mfma_f32_32x32x16_bf16 v[0:15], v[162:165], v[78:81], v[0:15]
	s_waitcnt lgkmcnt(8)
	v_mfma_f32_32x32x16_bf16 v[16:31], v[166:169], v[78:81], v[16:31]
	v_fmamk_f32 v86, v86, 0x3e38aa3b, v234
	v_fmamk_f32 v87, v87, 0x3e38aa3b, v234
	v_fmamk_f32 v88, v88, 0x3e38aa3b, v234
	v_fmamk_f32 v89, v89, 0x3e38aa3b, v234
	v_fmamk_f32 v90, v90, 0x3e38aa3b, v234
	v_fmamk_f32 v91, v91, 0x3e38aa3b, v234
	v_fmamk_f32 v92, v92, 0x3e38aa3b, v234
	v_fmamk_f32 v93, v93, 0x3e38aa3b, v234
	v_exp_f32_e32 v86, v86
	v_exp_f32_e32 v87, v87
	v_exp_f32_e32 v88, v88
	v_exp_f32_e32 v89, v89
	v_exp_f32_e32 v90, v90
	v_exp_f32_e32 v91, v91
	v_exp_f32_e32 v92, v92
	v_exp_f32_e32 v93, v93
	v_add_f32_e32 v243, v243, v86
	v_add_f32_e32 v244, v244, v87
	v_add_f32_e32 v245, v245, v88
	v_add_f32_e32 v246, v246, v89
	v_add_f32_e32 v243, v243, v90
	v_add_f32_e32 v244, v244, v91
	v_add_f32_e32 v245, v245, v92
	v_add_f32_e32 v246, v246, v93
	v_cvt_pk_bf16_f32 v86, v86, v87
	v_cvt_pk_bf16_f32 v87, v88, v89
	v_cvt_pk_bf16_f32 v88, v90, v91
	v_cvt_pk_bf16_f32 v89, v92, v93
	s_waitcnt lgkmcnt(6)
	v_mfma_f32_32x32x16_bf16 v[0:15], v[170:173], v[86:89], v[0:15]
	s_waitcnt lgkmcnt(4)
	v_mfma_f32_32x32x16_bf16 v[16:31], v[174:177], v[86:89], v[16:31]
	v_fmamk_f32 v94, v94, 0x3e38aa3b, v234
	v_fmamk_f32 v95, v95, 0x3e38aa3b, v234
	v_fmamk_f32 v96, v96, 0x3e38aa3b, v234
	v_fmamk_f32 v97, v97, 0x3e38aa3b, v234
	v_fmamk_f32 v98, v98, 0x3e38aa3b, v234
	v_fmamk_f32 v99, v99, 0x3e38aa3b, v234
	v_fmamk_f32 v100, v100, 0x3e38aa3b, v234
	v_fmamk_f32 v101, v101, 0x3e38aa3b, v234
	v_exp_f32_e32 v94, v94
	v_exp_f32_e32 v95, v95
	v_exp_f32_e32 v96, v96
	v_exp_f32_e32 v97, v97
	v_exp_f32_e32 v98, v98
	v_exp_f32_e32 v99, v99
	v_exp_f32_e32 v100, v100
	v_exp_f32_e32 v101, v101
	v_add_f32_e32 v243, v243, v94
	v_add_f32_e32 v244, v244, v95
	v_add_f32_e32 v245, v245, v96
	v_add_f32_e32 v246, v246, v97
	v_add_f32_e32 v243, v243, v98
	v_add_f32_e32 v244, v244, v99
	v_add_f32_e32 v245, v245, v100
	v_add_f32_e32 v246, v246, v101
	v_cvt_pk_bf16_f32 v94, v94, v95
	v_cvt_pk_bf16_f32 v95, v96, v97
	v_cvt_pk_bf16_f32 v96, v98, v99
	v_cvt_pk_bf16_f32 v97, v100, v101
	v_add_f32_e32 v243, v243, v244
	v_add_f32_e32 v245, v245, v246
	v_add_f32_e32 v243, v243, v245
	v_fma_f32 v231, v231, v232, v243
	s_waitcnt lgkmcnt(2)
	v_mfma_f32_32x32x16_bf16 v[0:15], v[178:181], v[94:97], v[0:15]
	s_waitcnt lgkmcnt(0)
	v_mfma_f32_32x32x16_bf16 v[16:31], v[182:185], v[94:97], v[16:31]
	s_waitcnt vmcnt(2)
	s_barrier
	s_cmp_lt_u32 s3, 4
	s_cbranch_scc1 .Lat_nd_l1
	s_nop 7
	s_nop 7
	s_nop 7
	s_nop 7

.Lat_nors_f2:
	v_fmamk_f32 v34, v34, 0x3e38aa3b, v234
	v_fmamk_f32 v35, v35, 0x3e38aa3b, v234
	s_waitcnt lgkmcnt(7)
	v_mfma_f32_32x32x16_bf16 v[70:85], v[118:121], v[102:105], 0
	ds_read_b64_tr_b16 v[154:155], v227 offset:16384
	ds_read_b64_tr_b16 v[156:157], v227 offset:17408
	v_fmamk_f32 v36, v36, 0x3e38aa3b, v234
	v_fmamk_f32 v37, v37, 0x3e38aa3b, v234
	v_fmamk_f32 v38, v38, 0x3e38aa3b, v234
	v_fmamk_f32 v39, v39, 0x3e38aa3b, v234
	v_fmamk_f32 v40, v40, 0x3e38aa3b, v234
	v_fmamk_f32 v41, v41, 0x3e38aa3b, v234
	v_exp_f32_e32 v34, v34
	v_exp_f32_e32 v35, v35
	v_exp_f32_e32 v36, v36
	v_exp_f32_e32 v37, v37
	v_exp_f32_e32 v38, v38
	v_exp_f32_e32 v39, v39
	s_waitcnt lgkmcnt(8)
	v_mfma_f32_32x32x16_bf16 v[86:101], v[122:125], v[102:105], 0
	ds_read_b64_tr_b16 v[158:159], v228 offset:16384
	ds_read_b64_tr_b16 v[160:161], v228 offset:17408
	v_exp_f32_e32 v40, v40
	v_exp_f32_e32 v41, v41
	v_add_f32_e32 v243, v34, v38
	v_add_f32_e32 v244, v35, v39
	v_add_f32_e32 v245, v36, v40
	v_add_f32_e32 v246, v37, v41
	v_cvt_pk_bf16_f32 v34, v34, v35
	v_cvt_pk_bf16_f32 v35, v36, v37
	v_cvt_pk_bf16_f32 v36, v38, v39
	v_cvt_pk_bf16_f32 v37, v40, v41
	v_fmamk_f32 v42, v42, 0x3e38aa3b, v234
	v_fmamk_f32 v43, v43, 0x3e38aa3b, v234
	s_waitcnt lgkmcnt(9)
	v_mfma_f32_32x32x16_bf16 v[70:85], v[126:129], v[106:109], v[70:85]
	ds_read_b64_tr_b16 v[162:163], v227 offset:18432
	ds_read_b64_tr_b16 v[164:165], v227 offset:19456
	v_fmamk_f32 v44, v44, 0x3e38aa3b, v234
	v_fmamk_f32 v45, v45, 0x3e38aa3b, v234
	v_fmamk_f32 v46, v46, 0x3e38aa3b, v234
	v_fmamk_f32 v47, v47, 0x3e38aa3b, v234
	v_fmamk_f32 v48, v48, 0x3e38aa3b, v234
	v_fmamk_f32 v49, v49, 0x3e38aa3b, v234
	v_exp_f32_e32 v42, v42
	v_exp_f32_e32 v43, v43
	v_exp_f32_e32 v44, v44
	v_exp_f32_e32 v45, v45
	v_exp_f32_e32 v46, v46
	v_exp_f32_e32 v47, v47
	s_waitcnt lgkmcnt(10)
	v_mfma_f32_32x32x16_bf16 v[86:101], v[130:133], v[106:109], v[86:101]
	ds_read_b64_tr_b16 v[166:167], v228 offset:18432
	ds_read_b64_tr_b16 v[168:169], v228 offset:19456
	v_exp_f32_e32 v48, v48
	v_exp_f32_e32 v49, v49
	v_add_f32_e32 v243, v243, v42
	v_add_f32_e32 v244, v244, v43
	v_add_f32_e32 v245, v245, v44
	v_add_f32_e32 v246, v246, v45
	v_add_f32_e32 v243, v243, v46
	v_add_f32_e32 v244, v244, v47
	v_add_f32_e32 v245, v245, v48
	v_add_f32_e32 v246, v246, v49
	v_cvt_pk_bf16_f32 v42, v42, v43
	v_cvt_pk_bf16_f32 v43, v44, v45
	s_waitcnt lgkmcnt(11)
	v_mfma_f32_32x32x16_bf16 v[70:85], v[134:137], v[110:113], v[70:85]
	ds_read_b64_tr_b16 v[170:171], v227 offset:20480
	ds_read_b64_tr_b16 v[172:173], v227 offset:21504
	v_cvt_pk_bf16_f32 v44, v46, v47
	v_cvt_pk_bf16_f32 v45, v48, v49
	v_fmamk_f32 v50, v50, 0x3e38aa3b, v234
	v_fmamk_f32 v51, v51, 0x3e38aa3b, v234
	v_fmamk_f32 v52, v52, 0x3e38aa3b, v234
	v_fmamk_f32 v53, v53, 0x3e38aa3b, v234
	v_fmamk_f32 v54, v54, 0x3e38aa3b, v234
	v_fmamk_f32 v55, v55, 0x3e38aa3b, v234
	v_fmamk_f32 v56, v56, 0x3e38aa3b, v234
	v_fmamk_f32 v57, v57, 0x3e38aa3b, v234
	v_exp_f32_e32 v50, v50
	v_exp_f32_e32 v51, v51
	s_waitcnt lgkmcnt(12)
	v_mfma_f32_32x32x16_bf16 v[86:101], v[138:141], v[110:113], v[86:101]
	ds_read_b64_tr_b16 v[174:175], v228 offset:20480
	ds_read_b64_tr_b16 v[176:177], v228 offset:21504
	v_exp_f32_e32 v52, v52
	v_exp_f32_e32 v53, v53
	v_exp_f32_e32 v54, v54
	v_exp_f32_e32 v55, v55
	v_exp_f32_e32 v56, v56
	v_exp_f32_e32 v57, v57
	v_add_f32_e32 v243, v243, v50
	v_add_f32_e32 v244, v244, v51
	v_add_f32_e32 v245, v245, v52
	v_add_f32_e32 v246, v246, v53
	v_add_f32_e32 v243, v243, v54
	v_add_f32_e32 v244, v244, v55
	s_waitcnt lgkmcnt(13)
	v_mfma_f32_32x32x16_bf16 v[70:85], v[142:145], v[114:117], v[70:85]
	ds_read_b64_tr_b16 v[178:179], v227 offset:22528
	ds_read_b64_tr_b16 v[180:181], v227 offset:23552
	v_add_f32_e32 v245, v245, v56
	v_add_f32_e32 v246, v246, v57
	v_cvt_pk_bf16_f32 v50, v50, v51
	v_cvt_pk_bf16_f32 v51, v52, v53
	v_cvt_pk_bf16_f32 v52, v54, v55
	v_cvt_pk_bf16_f32 v53, v56, v57
	v_fmamk_f32 v58, v58, 0x3e38aa3b, v234
	v_fmamk_f32 v59, v59, 0x3e38aa3b, v234
	v_fmamk_f32 v60, v60, 0x3e38aa3b, v234
	v_fmamk_f32 v61, v61, 0x3e38aa3b, v234
	v_fmamk_f32 v62, v62, 0x3e38aa3b, v234
	v_fmamk_f32 v63, v63, 0x3e38aa3b, v234
	s_waitcnt lgkmcnt(14)
	v_mfma_f32_32x32x16_bf16 v[86:101], v[146:149], v[114:117], v[86:101]
	ds_read_b64_tr_b16 v[182:183], v228 offset:22528
	ds_read_b64_tr_b16 v[184:185], v228 offset:23552
	s_waitcnt lgkmcnt(14)
	v_fmamk_f32 v64, v64, 0x3e38aa3b, v234
	v_fmamk_f32 v65, v65, 0x3e38aa3b, v234
	v_exp_f32_e32 v58, v58
	v_exp_f32_e32 v59, v59
	v_exp_f32_e32 v60, v60
	v_exp_f32_e32 v61, v61
	v_exp_f32_e32 v62, v62
	v_exp_f32_e32 v63, v63
	v_exp_f32_e32 v64, v64
	v_exp_f32_e32 v65, v65
	v_add_f32_e32 v243, v243, v58
	v_add_f32_e32 v244, v244, v59
	v_add_f32_e32 v245, v245, v60
	v_add_f32_e32 v246, v246, v61
	s_waitcnt lgkmcnt(14)
	v_mfma_f32_32x32x16_bf16 v[0:15], v[154:157], v[34:37], v[0:15]
	ds_read_b128 v[118:121], v223 offset:0
	v_add_f32_e32 v243, v243, v62
	v_add_f32_e32 v244, v244, v63
	v_add_f32_e32 v245, v245, v64
	v_add_f32_e32 v246, v246, v65
	v_cvt_pk_bf16_f32 v58, v58, v59
	v_cvt_pk_bf16_f32 v59, v60, v61
	v_cvt_pk_bf16_f32 v60, v62, v63
	v_cvt_pk_bf16_f32 v61, v64, v65
	v_add_f32_e32 v243, v243, v244
	v_add_f32_e32 v245, v245, v246
	v_add_f32_e32 v243, v243, v245
	v_fma_f32 v231, v231, v232, v243
	s_waitcnt lgkmcnt(13)
	v_mfma_f32_32x32x16_bf16 v[16:31], v[158:161], v[34:37], v[16:31]
	ds_read_b128 v[122:125], v223 offset:4096
	v_lshrrev_b32_e32 v249, v229, v204
	v_lshrrev_b32_e32 v250, v229, v205
	v_bfe_i32 v235, v249, 0, 1
	v_bfe_i32 v236, v250, 0, 1
	v_bfe_i32 v237, v249, 1, 1
	v_bfe_i32 v238, v250, 1, 1
	v_bfe_i32 v239, v249, 2, 1
	v_bfe_i32 v240, v250, 2, 1
	v_bfe_i32 v241, v249, 3, 1
	v_bfe_i32 v242, v250, 3, 1
	v_bitop3_b32 v70, v70, s33, v235 bitop3:0xe4
	s_waitcnt lgkmcnt(12)
	v_mfma_f32_32x32x16_bf16 v[0:15], v[162:165], v[42:45], v[0:15]
	ds_read_b128 v[126:129], v224 offset:0
	v_bitop3_b32 v86, v86, s33, v236 bitop3:0xe4
	v_bitop3_b32 v71, v71, s33, v237 bitop3:0xe4
	v_bitop3_b32 v87, v87, s33, v238 bitop3:0xe4
	v_bitop3_b32 v72, v72, s33, v239 bitop3:0xe4
	v_bitop3_b32 v88, v88, s33, v240 bitop3:0xe4
	v_bitop3_b32 v73, v73, s33, v241 bitop3:0xe4
	v_bitop3_b32 v89, v89, s33, v242 bitop3:0xe4
	v_max3_f32 v247, v70, s33, v86
	v_max3_f32 v248, v71, s33, v87
	v_max3_f32 v247, v247, v72, v88
	v_max3_f32 v248, v248, v73, v89
	v_bfe_i32 v235, v249, 8, 1
	s_waitcnt lgkmcnt(11)
	v_mfma_f32_32x32x16_bf16 v[16:31], v[166:169], v[42:45], v[16:31]
	ds_read_b128 v[130:133], v224 offset:4096
	v_bfe_i32 v236, v250, 8, 1
	v_bfe_i32 v237, v249, 9, 1
	v_bfe_i32 v238, v250, 9, 1
	v_bfe_i32 v239, v249, 10, 1
	v_bfe_i32 v240, v250, 10, 1
	v_bfe_i32 v241, v249, 11, 1
	v_bfe_i32 v242, v250, 11, 1
	v_bitop3_b32 v74, v74, s33, v235 bitop3:0xe4
	v_bitop3_b32 v90, v90, s33, v236 bitop3:0xe4
	v_bitop3_b32 v75, v75, s33, v237 bitop3:0xe4
	v_bitop3_b32 v91, v91, s33, v238 bitop3:0xe4
	v_bitop3_b32 v76, v76, s33, v239 bitop3:0xe4
	s_waitcnt lgkmcnt(10)
	v_mfma_f32_32x32x16_bf16 v[0:15], v[170:173], v[50:53], v[0:15]
	ds_read_b128 v[134:137], v225 offset:0
	v_bitop3_b32 v92, v92, s33, v240 bitop3:0xe4
	v_bitop3_b32 v77, v77, s33, v241 bitop3:0xe4
	v_bitop3_b32 v93, v93, s33, v242 bitop3:0xe4
	v_max3_f32 v247, v247, v74, v90
	v_max3_f32 v248, v248, v75, v91
	v_max3_f32 v247, v247, v76, v92
	v_max3_f32 v248, v248, v77, v93
	v_bfe_i32 v235, v249, 16, 1
	v_bfe_i32 v236, v250, 16, 1
	v_bfe_i32 v237, v249, 17, 1
	v_bfe_i32 v238, v250, 17, 1
	v_bfe_i32 v239, v249, 18, 1
	s_waitcnt lgkmcnt(9)
	v_mfma_f32_32x32x16_bf16 v[16:31], v[174:177], v[50:53], v[16:31]
	ds_read_b128 v[138:141], v225 offset:4096
	v_bfe_i32 v240, v250, 18, 1
	v_bfe_i32 v241, v249, 19, 1
	v_bfe_i32 v242, v250, 19, 1
	v_bitop3_b32 v78, v78, s33, v235 bitop3:0xe4
	v_bitop3_b32 v94, v94, s33, v236 bitop3:0xe4
	v_bitop3_b32 v79, v79, s33, v237 bitop3:0xe4
	v_bitop3_b32 v95, v95, s33, v238 bitop3:0xe4
	v_bitop3_b32 v80, v80, s33, v239 bitop3:0xe4
	v_bitop3_b32 v96, v96, s33, v240 bitop3:0xe4
	v_bitop3_b32 v81, v81, s33, v241 bitop3:0xe4
	v_bitop3_b32 v97, v97, s33, v242 bitop3:0xe4
	v_max3_f32 v247, v247, v78, v94
	s_waitcnt lgkmcnt(8)
	v_mfma_f32_32x32x16_bf16 v[0:15], v[178:181], v[58:61], v[0:15]
	ds_read_b128 v[142:145], v226 offset:0
	v_max3_f32 v248, v248, v79, v95
	v_max3_f32 v247, v247, v80, v96
	v_max3_f32 v248, v248, v81, v97
	v_bfe_i32 v235, v249, 24, 1
	v_bfe_i32 v236, v250, 24, 1
	v_bfe_i32 v237, v249, 25, 1
	v_bfe_i32 v238, v250, 25, 1
	v_bfe_i32 v239, v249, 26, 1
	v_bfe_i32 v240, v250, 26, 1
	v_bfe_i32 v241, v249, 27, 1
	v_bfe_i32 v242, v250, 27, 1
	v_bitop3_b32 v82, v82, s33, v235 bitop3:0xe4
	s_waitcnt lgkmcnt(7)
	v_mfma_f32_32x32x16_bf16 v[16:31], v[182:185], v[58:61], v[16:31]
	ds_read_b128 v[146:149], v226 offset:4096
	v_bitop3_b32 v98, v98, s33, v236 bitop3:0xe4
	v_bitop3_b32 v83, v83, s33, v237 bitop3:0xe4
	v_bitop3_b32 v99, v99, s33, v238 bitop3:0xe4
	v_bitop3_b32 v84, v84, s33, v239 bitop3:0xe4
	v_bitop3_b32 v100, v100, s33, v240 bitop3:0xe4
	v_bitop3_b32 v85, v85, s33, v241 bitop3:0xe4
	v_bitop3_b32 v101, v101, s33, v242 bitop3:0xe4
	v_max3_f32 v247, v247, v82, v98
	v_max3_f32 v248, v248, v83, v99
	v_max3_f32 v247, v247, v84, v100
	v_max3_f32 v248, v248, v85, v101
	v_max_f32_e32 v247, v247, v248
	v_mov_b32_e32 v248, v247
	s_nop 1
	v_permlane32_swap_b32_e32 v247, v248
	v_max3_f32 v247, v230, v247, v248
	v_cmp_neq_f32_e32 vcc, s33, v247
	s_nop 1
	v_cndmask_b32_e32 v248, 0, v247, vcc
	v_sub_f32_e32 v33, v230, v248
	v_mul_f32_e32 v33, 0x3e38aa3b, v33
	v_exp_f32_e32 v232, v33
	v_mul_f32_e32 v234, 0xbe38aa3b, v248
	v_mov_b32_e32 v230, v247
	s_waitcnt vmcnt(3)
	s_barrier
	s_cmp_lt_u32 s3, 4
	s_cbranch_scc1 .Lat_nd_f2
	s_nop 7
	s_nop 7
	s_nop 7
	s_nop 7

.Lat_nors_l2:
	v_fmamk_f32 v34, v34, 0x3e38aa3b, v234
	v_fmamk_f32 v35, v35, 0x3e38aa3b, v234
	v_fmamk_f32 v36, v36, 0x3e38aa3b, v234
	ds_read_b64_tr_b16 v[168:169], v228 offset:19456
	s_waitcnt lgkmcnt(14)
	v_fmamk_f32 v37, v37, 0x3e38aa3b, v234
	v_fmamk_f32 v38, v38, 0x3e38aa3b, v234
	v_fmamk_f32 v39, v39, 0x3e38aa3b, v234
	ds_read_b64_tr_b16 v[170:171], v227 offset:20480
	s_waitcnt lgkmcnt(14)
	v_fmamk_f32 v40, v40, 0x3e38aa3b, v234
	v_fmamk_f32 v41, v41, 0x3e38aa3b, v234
	v_exp_f32_e32 v34, v34
	ds_read_b64_tr_b16 v[172:173], v227 offset:21504
	s_waitcnt lgkmcnt(14)
	v_exp_f32_e32 v35, v35
	v_exp_f32_e32 v36, v36
	v_exp_f32_e32 v37, v37
	ds_read_b64_tr_b16 v[174:175], v228 offset:20480
	s_waitcnt lgkmcnt(14)
	v_exp_f32_e32 v38, v38
	v_exp_f32_e32 v39, v39
	v_exp_f32_e32 v40, v40
	ds_read_b64_tr_b16 v[176:177], v228 offset:21504
	s_waitcnt lgkmcnt(14)
	v_exp_f32_e32 v41, v41
	v_add_f32_e32 v243, v34, v38
	v_add_f32_e32 v244, v35, v39
	ds_read_b64_tr_b16 v[178:179], v227 offset:22528
	s_waitcnt lgkmcnt(14)
	v_add_f32_e32 v245, v36, v40
	v_add_f32_e32 v246, v37, v41
	v_cvt_pk_bf16_f32 v34, v34, v35
	ds_read_b64_tr_b16 v[180:181], v227 offset:23552
	s_waitcnt lgkmcnt(14)
	v_cvt_pk_bf16_f32 v35, v36, v37
	v_cvt_pk_bf16_f32 v36, v38, v39
	v_cvt_pk_bf16_f32 v37, v40, v41
	ds_read_b64_tr_b16 v[182:183], v228 offset:22528
	s_waitcnt lgkmcnt(14)
	s_waitcnt lgkmcnt(13)
	v_mfma_f32_32x32x16_bf16 v[0:15], v[154:157], v[34:37], v[0:15]
	s_waitcnt lgkmcnt(11)
	v_mfma_f32_32x32x16_bf16 v[16:31], v[158:161], v[34:37], v[16:31]
	v_fmamk_f32 v42, v42, 0x3e38aa3b, v234
	v_fmamk_f32 v43, v43, 0x3e38aa3b, v234
	v_fmamk_f32 v44, v44, 0x3e38aa3b, v234
	ds_read_b64_tr_b16 v[184:185], v228 offset:23552
	v_fmamk_f32 v45, v45, 0x3e38aa3b, v234
	v_fmamk_f32 v46, v46, 0x3e38aa3b, v234
	v_fmamk_f32 v47, v47, 0x3e38aa3b, v234
	v_fmamk_f32 v48, v48, 0x3e38aa3b, v234
	v_fmamk_f32 v49, v49, 0x3e38aa3b, v234
	v_exp_f32_e32 v42, v42
	v_exp_f32_e32 v43, v43
	v_exp_f32_e32 v44, v44
	v_exp_f32_e32 v45, v45
	v_exp_f32_e32 v46, v46
	v_exp_f32_e32 v47, v47
	v_exp_f32_e32 v48, v48
	v_exp_f32_e32 v49, v49
	v_add_f32_e32 v243, v243, v42
	v_add_f32_e32 v244, v244, v43
	v_add_f32_e32 v245, v245, v44
	v_add_f32_e32 v246, v246, v45
	v_add_f32_e32 v243, v243, v46
	v_add_f32_e32 v244, v244, v47
	v_add_f32_e32 v245, v245, v48
	v_add_f32_e32 v246, v246, v49
	v_cvt_pk_bf16_f32 v42, v42, v43
	v_cvt_pk_bf16_f32 v43, v44, v45
	v_cvt_pk_bf16_f32 v44, v46, v47
	v_cvt_pk_bf16_f32 v45, v48, v49
	s_waitcnt lgkmcnt(10)
	v_mfma_f32_32x32x16_bf16 v[0:15], v[162:165], v[42:45], v[0:15]
	s_waitcnt lgkmcnt(8)
	v_mfma_f32_32x32x16_bf16 v[16:31], v[166:169], v[42:45], v[16:31]
	v_fmamk_f32 v50, v50, 0x3e38aa3b, v234
	v_fmamk_f32 v51, v51, 0x3e38aa3b, v234
	v_fmamk_f32 v52, v52, 0x3e38aa3b, v234
	v_fmamk_f32 v53, v53, 0x3e38aa3b, v234
	v_fmamk_f32 v54, v54, 0x3e38aa3b, v234
	v_fmamk_f32 v55, v55, 0x3e38aa3b, v234
	v_fmamk_f32 v56, v56, 0x3e38aa3b, v234
	v_fmamk_f32 v57, v57, 0x3e38aa3b, v234
	v_exp_f32_e32 v50, v50
	v_exp_f32_e32 v51, v51
	v_exp_f32_e32 v52, v52
	v_exp_f32_e32 v53, v53
	v_exp_f32_e32 v54, v54
	v_exp_f32_e32 v55, v55
	v_exp_f32_e32 v56, v56
	v_exp_f32_e32 v57, v57
	v_add_f32_e32 v243, v243, v50
	v_add_f32_e32 v244, v244, v51
	v_add_f32_e32 v245, v245, v52
	v_add_f32_e32 v246, v246, v53
	v_add_f32_e32 v243, v243, v54
	v_add_f32_e32 v244, v244, v55
	v_add_f32_e32 v245, v245, v56
	v_add_f32_e32 v246, v246, v57
	v_cvt_pk_bf16_f32 v50, v50, v51
	v_cvt_pk_bf16_f32 v51, v52, v53
	v_cvt_pk_bf16_f32 v52, v54, v55
	v_cvt_pk_bf16_f32 v53, v56, v57
	s_waitcnt lgkmcnt(6)
	v_mfma_f32_32x32x16_bf16 v[0:15], v[170:173], v[50:53], v[0:15]
	s_waitcnt lgkmcnt(4)
	v_mfma_f32_32x32x16_bf16 v[16:31], v[174:177], v[50:53], v[16:31]
	v_fmamk_f32 v58, v58, 0x3e38aa3b, v234
	v_fmamk_f32 v59, v59, 0x3e38aa3b, v234
	v_fmamk_f32 v60, v60, 0x3e38aa3b, v234
	v_fmamk_f32 v61, v61, 0x3e38aa3b, v234
	v_fmamk_f32 v62, v62, 0x3e38aa3b, v234
	v_fmamk_f32 v63, v63, 0x3e38aa3b, v234
	v_fmamk_f32 v64, v64, 0x3e38aa3b, v234
	v_fmamk_f32 v65, v65, 0x3e38aa3b, v234
	v_exp_f32_e32 v58, v58
	v_exp_f32_e32 v59, v59
	v_exp_f32_e32 v60, v60
	v_exp_f32_e32 v61, v61
	v_exp_f32_e32 v62, v62
	v_exp_f32_e32 v63, v63
	v_exp_f32_e32 v64, v64
	v_exp_f32_e32 v65, v65
	v_add_f32_e32 v243, v243, v58
	v_add_f32_e32 v244, v244, v59
	v_add_f32_e32 v245, v245, v60
	v_add_f32_e32 v246, v246, v61
	v_add_f32_e32 v243, v243, v62
	v_add_f32_e32 v244, v244, v63
	v_add_f32_e32 v245, v245, v64
	v_add_f32_e32 v246, v246, v65
	v_cvt_pk_bf16_f32 v58, v58, v59
	v_cvt_pk_bf16_f32 v59, v60, v61
	v_cvt_pk_bf16_f32 v60, v62, v63
	v_cvt_pk_bf16_f32 v61, v64, v65
	v_add_f32_e32 v243, v243, v244
	v_add_f32_e32 v245, v245, v246
	v_add_f32_e32 v243, v243, v245
	v_fma_f32 v231, v231, v232, v243
	s_waitcnt lgkmcnt(2)
	v_mfma_f32_32x32x16_bf16 v[0:15], v[178:181], v[58:61], v[0:15]
	s_waitcnt lgkmcnt(0)
	v_mfma_f32_32x32x16_bf16 v[16:31], v[182:185], v[58:61], v[16:31]
	s_waitcnt vmcnt(3)
	s_barrier
	s_cmp_lt_u32 s3, 4
	s_cbranch_scc1 .Lat_nd_l2
	s_nop 7
	s_nop 7
	s_nop 7
	s_nop 7

.Lat_nors_f3:
	v_fmamk_f32 v70, v70, 0x3e38aa3b, v234
	v_fmamk_f32 v71, v71, 0x3e38aa3b, v234
	s_waitcnt lgkmcnt(7)
	v_mfma_f32_32x32x16_bf16 v[34:49], v[118:121], v[102:105], 0
	ds_read_b64_tr_b16 v[154:155], v227 offset:24576
	ds_read_b64_tr_b16 v[156:157], v227 offset:25600
	v_fmamk_f32 v72, v72, 0x3e38aa3b, v234
	v_fmamk_f32 v73, v73, 0x3e38aa3b, v234
	v_fmamk_f32 v74, v74, 0x3e38aa3b, v234
	v_fmamk_f32 v75, v75, 0x3e38aa3b, v234
	v_fmamk_f32 v76, v76, 0x3e38aa3b, v234
	v_fmamk_f32 v77, v77, 0x3e38aa3b, v234
	v_exp_f32_e32 v70, v70
	v_exp_f32_e32 v71, v71
	v_exp_f32_e32 v72, v72
	v_exp_f32_e32 v73, v73
	v_exp_f32_e32 v74, v74
	v_exp_f32_e32 v75, v75
	s_waitcnt lgkmcnt(8)
	v_mfma_f32_32x32x16_bf16 v[50:65], v[122:125], v[102:105], 0
	ds_read_b64_tr_b16 v[158:159], v228 offset:24576
	ds_read_b64_tr_b16 v[160:161], v228 offset:25600
	v_exp_f32_e32 v76, v76
	v_exp_f32_e32 v77, v77
	v_add_f32_e32 v243, v70, v74
	v_add_f32_e32 v244, v71, v75
	v_add_f32_e32 v245, v72, v76
	v_add_f32_e32 v246, v73, v77
	v_cvt_pk_bf16_f32 v70, v70, v71
	v_cvt_pk_bf16_f32 v71, v72, v73
	v_cvt_pk_bf16_f32 v72, v74, v75
	v_cvt_pk_bf16_f32 v73, v76, v77
	v_fmamk_f32 v78, v78, 0x3e38aa3b, v234
	v_fmamk_f32 v79, v79, 0x3e38aa3b, v234
	s_waitcnt lgkmcnt(9)
	v_mfma_f32_32x32x16_bf16 v[34:49], v[126:129], v[106:109], v[34:49]
	ds_read_b64_tr_b16 v[162:163], v227 offset:26624
	ds_read_b64_tr_b16 v[164:165], v227 offset:27648
	v_fmamk_f32 v80, v80, 0x3e38aa3b, v234
	v_fmamk_f32 v81, v81, 0x3e38aa3b, v234
	v_fmamk_f32 v82, v82, 0x3e38aa3b, v234
	v_fmamk_f32 v83, v83, 0x3e38aa3b, v234
	v_fmamk_f32 v84, v84, 0x3e38aa3b, v234
	v_fmamk_f32 v85, v85, 0x3e38aa3b, v234
	v_exp_f32_e32 v78, v78
	v_exp_f32_e32 v79, v79
	v_exp_f32_e32 v80, v80
	v_exp_f32_e32 v81, v81
	v_exp_f32_e32 v82, v82
	v_exp_f32_e32 v83, v83
	s_waitcnt lgkmcnt(10)
	v_mfma_f32_32x32x16_bf16 v[50:65], v[130:133], v[106:109], v[50:65]
	ds_read_b64_tr_b16 v[166:167], v228 offset:26624
	ds_read_b64_tr_b16 v[168:169], v228 offset:27648
	v_exp_f32_e32 v84, v84
	v_exp_f32_e32 v85, v85
	v_add_f32_e32 v243, v243, v78
	v_add_f32_e32 v244, v244, v79
	v_add_f32_e32 v245, v245, v80
	v_add_f32_e32 v246, v246, v81
	v_add_f32_e32 v243, v243, v82
	v_add_f32_e32 v244, v244, v83
	v_add_f32_e32 v245, v245, v84
	v_add_f32_e32 v246, v246, v85
	v_cvt_pk_bf16_f32 v78, v78, v79
	v_cvt_pk_bf16_f32 v79, v80, v81
	s_waitcnt lgkmcnt(11)
	v_mfma_f32_32x32x16_bf16 v[34:49], v[134:137], v[110:113], v[34:49]
	ds_read_b64_tr_b16 v[170:171], v227 offset:28672
	ds_read_b64_tr_b16 v[172:173], v227 offset:29696
	v_cvt_pk_bf16_f32 v80, v82, v83
	v_cvt_pk_bf16_f32 v81, v84, v85
	v_fmamk_f32 v86, v86, 0x3e38aa3b, v234
	v_fmamk_f32 v87, v87, 0x3e38aa3b, v234
	v_fmamk_f32 v88, v88, 0x3e38aa3b, v234
	v_fmamk_f32 v89, v89, 0x3e38aa3b, v234
	v_fmamk_f32 v90, v90, 0x3e38aa3b, v234
	v_fmamk_f32 v91, v91, 0x3e38aa3b, v234
	v_fmamk_f32 v92, v92, 0x3e38aa3b, v234
	v_fmamk_f32 v93, v93, 0x3e38aa3b, v234
	v_exp_f32_e32 v86, v86
	v_exp_f32_e32 v87, v87
	s_waitcnt lgkmcnt(12)
	v_mfma_f32_32x32x16_bf16 v[50:65], v[138:141], v[110:113], v[50:65]
	ds_read_b64_tr_b16 v[174:175], v228 offset:28672
	ds_read_b64_tr_b16 v[176:177], v228 offset:29696
	v_exp_f32_e32 v88, v88
	v_exp_f32_e32 v89, v89
	v_exp_f32_e32 v90, v90
	v_exp_f32_e32 v91, v91
	v_exp_f32_e32 v92, v92
	v_exp_f32_e32 v93, v93
	v_add_f32_e32 v243, v243, v86
	v_add_f32_e32 v244, v244, v87
	v_add_f32_e32 v245, v245, v88
	v_add_f32_e32 v246, v246, v89
	v_add_f32_e32 v243, v243, v90
	v_add_f32_e32 v244, v244, v91
	s_waitcnt lgkmcnt(13)
	v_mfma_f32_32x32x16_bf16 v[34:49], v[142:145], v[114:117], v[34:49]
	ds_read_b64_tr_b16 v[178:179], v227 offset:30720
	ds_read_b64_tr_b16 v[180:181], v227 offset:31744
	v_add_f32_e32 v245, v245, v92
	v_add_f32_e32 v246, v246, v93
	v_cvt_pk_bf16_f32 v86, v86, v87
	v_cvt_pk_bf16_f32 v87, v88, v89
	v_cvt_pk_bf16_f32 v88, v90, v91
	v_cvt_pk_bf16_f32 v89, v92, v93
	v_fmamk_f32 v94, v94, 0x3e38aa3b, v234
	v_fmamk_f32 v95, v95, 0x3e38aa3b, v234
	v_fmamk_f32 v96, v96, 0x3e38aa3b, v234
	v_fmamk_f32 v97, v97, 0x3e38aa3b, v234
	v_fmamk_f32 v98, v98, 0x3e38aa3b, v234
	v_fmamk_f32 v99, v99, 0x3e38aa3b, v234
	s_waitcnt lgkmcnt(14)
	v_mfma_f32_32x32x16_bf16 v[50:65], v[146:149], v[114:117], v[50:65]
	ds_read_b64_tr_b16 v[182:183], v228 offset:30720
	ds_read_b64_tr_b16 v[184:185], v228 offset:31744
	s_waitcnt lgkmcnt(14)
	v_fmamk_f32 v100, v100, 0x3e38aa3b, v234
	v_fmamk_f32 v101, v101, 0x3e38aa3b, v234
	v_exp_f32_e32 v94, v94
	v_exp_f32_e32 v95, v95
	v_exp_f32_e32 v96, v96
	v_exp_f32_e32 v97, v97
	v_exp_f32_e32 v98, v98
	v_exp_f32_e32 v99, v99
	v_exp_f32_e32 v100, v100
	v_exp_f32_e32 v101, v101
	v_add_f32_e32 v243, v243, v94
	v_add_f32_e32 v244, v244, v95
	v_add_f32_e32 v245, v245, v96
	v_add_f32_e32 v246, v246, v97
	s_waitcnt lgkmcnt(14)
	v_mfma_f32_32x32x16_bf16 v[0:15], v[154:157], v[70:73], v[0:15]
	ds_read_b128 v[118:121], v223 offset:8192
	v_add_f32_e32 v243, v243, v98
	v_add_f32_e32 v244, v244, v99
	v_add_f32_e32 v245, v245, v100
	v_add_f32_e32 v246, v246, v101
	v_cvt_pk_bf16_f32 v94, v94, v95
	v_cvt_pk_bf16_f32 v95, v96, v97
	v_cvt_pk_bf16_f32 v96, v98, v99
	v_cvt_pk_bf16_f32 v97, v100, v101
	v_add_f32_e32 v243, v243, v244
	v_add_f32_e32 v245, v245, v246
	v_add_f32_e32 v243, v243, v245
	v_fma_f32 v231, v231, v232, v243
	s_waitcnt lgkmcnt(13)
	v_mfma_f32_32x32x16_bf16 v[16:31], v[158:161], v[70:73], v[16:31]
	ds_read_b128 v[122:125], v223 offset:12288
	s_waitcnt vmcnt(4)
	v_lshrrev_b32_e32 v249, v229, v198
	v_lshrrev_b32_e32 v250, v229, v199
	v_bfe_i32 v235, v249, 0, 1
	v_bfe_i32 v236, v250, 0, 1
	v_bfe_i32 v237, v249, 1, 1
	v_bfe_i32 v238, v250, 1, 1
	v_bfe_i32 v239, v249, 2, 1
	v_bfe_i32 v240, v250, 2, 1
	v_bfe_i32 v241, v249, 3, 1
	v_bfe_i32 v242, v250, 3, 1
	v_bitop3_b32 v34, v34, s33, v235 bitop3:0xe4
	s_waitcnt lgkmcnt(12)
	v_mfma_f32_32x32x16_bf16 v[0:15], v[162:165], v[78:81], v[0:15]
	ds_read_b128 v[126:129], v224 offset:8192
	v_bitop3_b32 v50, v50, s33, v236 bitop3:0xe4
	v_bitop3_b32 v35, v35, s33, v237 bitop3:0xe4
	v_bitop3_b32 v51, v51, s33, v238 bitop3:0xe4
	v_bitop3_b32 v36, v36, s33, v239 bitop3:0xe4
	v_bitop3_b32 v52, v52, s33, v240 bitop3:0xe4
	v_bitop3_b32 v37, v37, s33, v241 bitop3:0xe4
	v_bitop3_b32 v53, v53, s33, v242 bitop3:0xe4
	v_max3_f32 v247, v34, s33, v50
	v_max3_f32 v248, v35, s33, v51
	v_max3_f32 v247, v247, v36, v52
	v_max3_f32 v248, v248, v37, v53
	v_bfe_i32 v235, v249, 8, 1
	s_waitcnt lgkmcnt(11)
	v_mfma_f32_32x32x16_bf16 v[16:31], v[166:169], v[78:81], v[16:31]
	ds_read_b128 v[130:133], v224 offset:12288
	v_bfe_i32 v236, v250, 8, 1
	v_bfe_i32 v237, v249, 9, 1
	v_bfe_i32 v238, v250, 9, 1
	v_bfe_i32 v239, v249, 10, 1
	v_bfe_i32 v240, v250, 10, 1
	v_bfe_i32 v241, v249, 11, 1
	v_bfe_i32 v242, v250, 11, 1
	v_bitop3_b32 v38, v38, s33, v235 bitop3:0xe4
	v_bitop3_b32 v54, v54, s33, v236 bitop3:0xe4
	v_bitop3_b32 v39, v39, s33, v237 bitop3:0xe4
	v_bitop3_b32 v55, v55, s33, v238 bitop3:0xe4
	v_bitop3_b32 v40, v40, s33, v239 bitop3:0xe4
	s_waitcnt lgkmcnt(10)
	v_mfma_f32_32x32x16_bf16 v[0:15], v[170:173], v[86:89], v[0:15]
	ds_read_b128 v[134:137], v225 offset:8192
	v_bitop3_b32 v56, v56, s33, v240 bitop3:0xe4
	v_bitop3_b32 v41, v41, s33, v241 bitop3:0xe4
	v_bitop3_b32 v57, v57, s33, v242 bitop3:0xe4
	v_max3_f32 v247, v247, v38, v54
	v_max3_f32 v248, v248, v39, v55
	v_max3_f32 v247, v247, v40, v56
	v_max3_f32 v248, v248, v41, v57
	v_bfe_i32 v235, v249, 16, 1
	v_bfe_i32 v236, v250, 16, 1
	v_bfe_i32 v237, v249, 17, 1
	v_bfe_i32 v238, v250, 17, 1
	v_bfe_i32 v239, v249, 18, 1
	s_waitcnt lgkmcnt(9)
	v_mfma_f32_32x32x16_bf16 v[16:31], v[174:177], v[86:89], v[16:31]
	ds_read_b128 v[138:141], v225 offset:12288
	v_bfe_i32 v240, v250, 18, 1
	v_bfe_i32 v241, v249, 19, 1
	v_bfe_i32 v242, v250, 19, 1
	v_bitop3_b32 v42, v42, s33, v235 bitop3:0xe4
	v_bitop3_b32 v58, v58, s33, v236 bitop3:0xe4
	v_bitop3_b32 v43, v43, s33, v237 bitop3:0xe4
	v_bitop3_b32 v59, v59, s33, v238 bitop3:0xe4
	v_bitop3_b32 v44, v44, s33, v239 bitop3:0xe4
	v_bitop3_b32 v60, v60, s33, v240 bitop3:0xe4
	v_bitop3_b32 v45, v45, s33, v241 bitop3:0xe4
	v_bitop3_b32 v61, v61, s33, v242 bitop3:0xe4
	v_max3_f32 v247, v247, v42, v58
	s_waitcnt lgkmcnt(8)
	v_mfma_f32_32x32x16_bf16 v[0:15], v[178:181], v[94:97], v[0:15]
	ds_read_b128 v[142:145], v226 offset:8192
	v_max3_f32 v248, v248, v43, v59
	v_max3_f32 v247, v247, v44, v60
	v_max3_f32 v248, v248, v45, v61
	v_bfe_i32 v235, v249, 24, 1
	v_bfe_i32 v236, v250, 24, 1
	v_bfe_i32 v237, v249, 25, 1
	v_bfe_i32 v238, v250, 25, 1
	v_bfe_i32 v239, v249, 26, 1
	v_bfe_i32 v240, v250, 26, 1
	v_bfe_i32 v241, v249, 27, 1
	v_bfe_i32 v242, v250, 27, 1
	v_bitop3_b32 v46, v46, s33, v235 bitop3:0xe4
	s_waitcnt lgkmcnt(7)
	v_mfma_f32_32x32x16_bf16 v[16:31], v[182:185], v[94:97], v[16:31]
	ds_read_b128 v[146:149], v226 offset:12288
	v_bitop3_b32 v62, v62, s33, v236 bitop3:0xe4
	v_bitop3_b32 v47, v47, s33, v237 bitop3:0xe4
	v_bitop3_b32 v63, v63, s33, v238 bitop3:0xe4
	v_bitop3_b32 v48, v48, s33, v239 bitop3:0xe4
	v_bitop3_b32 v64, v64, s33, v240 bitop3:0xe4
	v_bitop3_b32 v49, v49, s33, v241 bitop3:0xe4
	v_bitop3_b32 v65, v65, s33, v242 bitop3:0xe4
	v_max3_f32 v247, v247, v46, v62
	v_max3_f32 v248, v248, v47, v63
	v_max3_f32 v247, v247, v48, v64
	v_max3_f32 v248, v248, v49, v65
	v_max_f32_e32 v247, v247, v248
	v_mov_b32_e32 v248, v247
	s_nop 1
	v_permlane32_swap_b32_e32 v247, v248
	v_max3_f32 v247, v230, v247, v248
	v_cmp_neq_f32_e32 vcc, s33, v247
	s_nop 1
	v_cndmask_b32_e32 v248, 0, v247, vcc
	v_sub_f32_e32 v33, v230, v248
	v_mul_f32_e32 v33, 0x3e38aa3b, v33
	v_exp_f32_e32 v232, v33
	v_mul_f32_e32 v234, 0xbe38aa3b, v248
	v_mov_b32_e32 v230, v247
	s_waitcnt vmcnt(2)
	s_barrier
	s_cmp_lt_u32 s3, 4
	s_cbranch_scc1 .Lat_nd_f3
	s_nop 7
	s_nop 7
	s_nop 7
	s_nop 7

.Lat_nors_l3:
	v_fmamk_f32 v70, v70, 0x3e38aa3b, v234
	v_fmamk_f32 v71, v71, 0x3e38aa3b, v234
	v_fmamk_f32 v72, v72, 0x3e38aa3b, v234
	ds_read_b64_tr_b16 v[168:169], v228 offset:27648
	s_waitcnt lgkmcnt(14)
	v_fmamk_f32 v73, v73, 0x3e38aa3b, v234
	v_fmamk_f32 v74, v74, 0x3e38aa3b, v234
	v_fmamk_f32 v75, v75, 0x3e38aa3b, v234
	ds_read_b64_tr_b16 v[170:171], v227 offset:28672
	s_waitcnt lgkmcnt(14)
	v_fmamk_f32 v76, v76, 0x3e38aa3b, v234
	v_fmamk_f32 v77, v77, 0x3e38aa3b, v234
	v_exp_f32_e32 v70, v70
	ds_read_b64_tr_b16 v[172:173], v227 offset:29696
	s_waitcnt lgkmcnt(14)
	v_exp_f32_e32 v71, v71
	v_exp_f32_e32 v72, v72
	v_exp_f32_e32 v73, v73
	ds_read_b64_tr_b16 v[174:175], v228 offset:28672
	s_waitcnt lgkmcnt(14)
	v_exp_f32_e32 v74, v74
	v_exp_f32_e32 v75, v75
	v_exp_f32_e32 v76, v76
	ds_read_b64_tr_b16 v[176:177], v228 offset:29696
	s_waitcnt lgkmcnt(14)
	v_exp_f32_e32 v77, v77
	v_add_f32_e32 v243, v70, v74
	v_add_f32_e32 v244, v71, v75
	ds_read_b64_tr_b16 v[178:179], v227 offset:30720
	s_waitcnt lgkmcnt(14)
	v_add_f32_e32 v245, v72, v76
	v_add_f32_e32 v246, v73, v77
	v_cvt_pk_bf16_f32 v70, v70, v71
	ds_read_b64_tr_b16 v[180:181], v227 offset:31744
	s_waitcnt lgkmcnt(14)
	v_cvt_pk_bf16_f32 v71, v72, v73
	v_cvt_pk_bf16_f32 v72, v74, v75
	v_cvt_pk_bf16_f32 v73, v76, v77
	ds_read_b64_tr_b16 v[182:183], v228 offset:30720
	s_waitcnt lgkmcnt(14)
	s_waitcnt lgkmcnt(13)
	v_mfma_f32_32x32x16_bf16 v[0:15], v[154:157], v[70:73], v[0:15]
	s_waitcnt lgkmcnt(11)
	v_mfma_f32_32x32x16_bf16 v[16:31], v[158:161], v[70:73], v[16:31]
	v_fmamk_f32 v78, v78, 0x3e38aa3b, v234
	v_fmamk_f32 v79, v79, 0x3e38aa3b, v234
	v_fmamk_f32 v80, v80, 0x3e38aa3b, v234
	ds_read_b64_tr_b16 v[184:185], v228 offset:31744
	v_fmamk_f32 v81, v81, 0x3e38aa3b, v234
	v_fmamk_f32 v82, v82, 0x3e38aa3b, v234
	v_fmamk_f32 v83, v83, 0x3e38aa3b, v234
	v_fmamk_f32 v84, v84, 0x3e38aa3b, v234
	v_fmamk_f32 v85, v85, 0x3e38aa3b, v234
	v_exp_f32_e32 v78, v78
	v_exp_f32_e32 v79, v79
	v_exp_f32_e32 v80, v80
	v_exp_f32_e32 v81, v81
	v_exp_f32_e32 v82, v82
	v_exp_f32_e32 v83, v83
	v_exp_f32_e32 v84, v84
	v_exp_f32_e32 v85, v85
	v_add_f32_e32 v243, v243, v78
	v_add_f32_e32 v244, v244, v79
	v_add_f32_e32 v245, v245, v80
	v_add_f32_e32 v246, v246, v81
	v_add_f32_e32 v243, v243, v82
	v_add_f32_e32 v244, v244, v83
	v_add_f32_e32 v245, v245, v84
	v_add_f32_e32 v246, v246, v85
	v_cvt_pk_bf16_f32 v78, v78, v79
	v_cvt_pk_bf16_f32 v79, v80, v81
	v_cvt_pk_bf16_f32 v80, v82, v83
	v_cvt_pk_bf16_f32 v81, v84, v85
	s_waitcnt lgkmcnt(10)
	v_mfma_f32_32x32x16_bf16 v[0:15], v[162:165], v[78:81], v[0:15]
	s_waitcnt lgkmcnt(8)
	v_mfma_f32_32x32x16_bf16 v[16:31], v[166:169], v[78:81], v[16:31]
	v_fmamk_f32 v86, v86, 0x3e38aa3b, v234
	v_fmamk_f32 v87, v87, 0x3e38aa3b, v234
	v_fmamk_f32 v88, v88, 0x3e38aa3b, v234
	v_fmamk_f32 v89, v89, 0x3e38aa3b, v234
	v_fmamk_f32 v90, v90, 0x3e38aa3b, v234
	v_fmamk_f32 v91, v91, 0x3e38aa3b, v234
	v_fmamk_f32 v92, v92, 0x3e38aa3b, v234
	v_fmamk_f32 v93, v93, 0x3e38aa3b, v234
	v_exp_f32_e32 v86, v86
	v_exp_f32_e32 v87, v87
	v_exp_f32_e32 v88, v88
	v_exp_f32_e32 v89, v89
	v_exp_f32_e32 v90, v90
	v_exp_f32_e32 v91, v91
	v_exp_f32_e32 v92, v92
	v_exp_f32_e32 v93, v93
	v_add_f32_e32 v243, v243, v86
	v_add_f32_e32 v244, v244, v87
	v_add_f32_e32 v245, v245, v88
	v_add_f32_e32 v246, v246, v89
	v_add_f32_e32 v243, v243, v90
	v_add_f32_e32 v244, v244, v91
	v_add_f32_e32 v245, v245, v92
	v_add_f32_e32 v246, v246, v93
	v_cvt_pk_bf16_f32 v86, v86, v87
	v_cvt_pk_bf16_f32 v87, v88, v89
	v_cvt_pk_bf16_f32 v88, v90, v91
	v_cvt_pk_bf16_f32 v89, v92, v93
	s_waitcnt lgkmcnt(6)
	v_mfma_f32_32x32x16_bf16 v[0:15], v[170:173], v[86:89], v[0:15]
	s_waitcnt lgkmcnt(4)
	v_mfma_f32_32x32x16_bf16 v[16:31], v[174:177], v[86:89], v[16:31]
	v_fmamk_f32 v94, v94, 0x3e38aa3b, v234
	v_fmamk_f32 v95, v95, 0x3e38aa3b, v234
	v_fmamk_f32 v96, v96, 0x3e38aa3b, v234
	v_fmamk_f32 v97, v97, 0x3e38aa3b, v234
	v_fmamk_f32 v98, v98, 0x3e38aa3b, v234
	v_fmamk_f32 v99, v99, 0x3e38aa3b, v234
	v_fmamk_f32 v100, v100, 0x3e38aa3b, v234
	v_fmamk_f32 v101, v101, 0x3e38aa3b, v234
	v_exp_f32_e32 v94, v94
	v_exp_f32_e32 v95, v95
	v_exp_f32_e32 v96, v96
	v_exp_f32_e32 v97, v97
	v_exp_f32_e32 v98, v98
	v_exp_f32_e32 v99, v99
	v_exp_f32_e32 v100, v100
	v_exp_f32_e32 v101, v101
	v_add_f32_e32 v243, v243, v94
	v_add_f32_e32 v244, v244, v95
	v_add_f32_e32 v245, v245, v96
	v_add_f32_e32 v246, v246, v97
	v_add_f32_e32 v243, v243, v98
	v_add_f32_e32 v244, v244, v99
	v_add_f32_e32 v245, v245, v100
	v_add_f32_e32 v246, v246, v101
	v_cvt_pk_bf16_f32 v94, v94, v95
	v_cvt_pk_bf16_f32 v95, v96, v97
	v_cvt_pk_bf16_f32 v96, v98, v99
	v_cvt_pk_bf16_f32 v97, v100, v101
	v_add_f32_e32 v243, v243, v244
	v_add_f32_e32 v245, v245, v246
	v_add_f32_e32 v243, v243, v245
	v_fma_f32 v231, v231, v232, v243
	s_waitcnt lgkmcnt(2)
	v_mfma_f32_32x32x16_bf16 v[0:15], v[178:181], v[94:97], v[0:15]
	s_waitcnt lgkmcnt(0)
	v_mfma_f32_32x32x16_bf16 v[16:31], v[182:185], v[94:97], v[16:31]
	s_waitcnt vmcnt(2)
	s_barrier
	s_cmp_lt_u32 s3, 4
	s_cbranch_scc1 .Lat_nd_l3
	s_nop 7
	s_nop 7
	s_nop 7
	s_nop 7
